# attention steady loop: half-step stagger of wave halves (waves 0-3 barrier between QK and PV parts, waves 4-7 at step end), V DMA retired within its step
# speedup vs baseline: 1.0023x; 1.0009x over previous
; #define WAIT_BAR(N) asm volatile("s_waitcnt vmcnt(" #N ") lgkmcnt(0)\n\ts_barrier":::"memory")
;   #define DMA_K(t,slot) glds16(ksrc+(long)(((t)+t0)&(NT-1))*KVBLK*KVP,(unsigned)__builtin_amdgcn_readfirstlane(kdst+(slot)))
;   #define DMA_V(t,slot) glds16(vsrc+(long)(((t)+t0)&(NT-1))*KVBLK*KVP,(unsigned)__builtin_amdgcn_readfirstlane(vdst+(slot)))
;   #define CMASK(P0,P1,t) do{}while(0)
;   #define CMASK(P0,P1,t) do{}while(0)
;   #define CMASK(P0,P1,t) do{}while(0)
; template<int THRL,bool NOMAX> __device__ __forceinline__ void attn_unit(int b,int h,int qb,int t0,const bf16*Q,const bf16*__restrict__ KV,const bf16*__restrict__ GA,bf16*O,char*shm){
;   int tid_=threadIdx.x; asm volatile("":"+v"(tid_)); const int tid=tid_,lane=tid&63,r32=lane&31,hi=lane>>5; const int wid=__builtin_amdgcn_readfirstlane(tid>>6);
;   const long rowbase=(long)b*SEQ; const int q0=qb*QB;
;   const bf16*Qw=Q+(rowbase+q0+wid*QBLK)*QP+h*D;
;   const int kvh=h>>2; const bf16*Kh=KV+rowbase*KVP+kvh*D,*Vh=KV+rowbase*KVP+128+kvh*D;
;   const unsigned lds0=(unsigned)(uintptr_t)shm;
;   float*wsf=(float*)(shm+LDS_WS)+wid*64;
;   const bf16*ksrc=Kh+(long)lane*KVP+wid*8;
;   const bf16*vsrc=Vh+(long)(16*(wid&3)+(lane>>2))*KVP+(wid>>2)*32+(lane&3)*8;
;   const unsigned kdst=lds0+LDS_K+wid*1024, vdst=lds0+LDS_V+wid*1024;
;     ...
;   const int vb0=(int)(lds0+LDS_V)+((lane>>4)&1)*32+(lane&3)*8+(4*hi+((lane&15)>>2))*64;
;   const char*Kbase=shm+LDS_K; bf16x8 kf[8];
;   const lds_cptr shm3=(lds_cptr)shm; const lds_cptr kp0=shm3+LDS_K+hi*1024+r32*16; const lds_cptr vp0=shm3+LDS_V+((lane>>4)&1)*32+(lane&3)*8+(4*hi+((lane&15)>>2))*64;
;   const int NT=SEQ/KVBLK;
;   DMA_K(0,0);DMA_V(0,0);DMA_K(1,SLOTB);
;   bf16x8 qr[4];
;   #pragma unroll
;   for(int d0=0;d0<4;++d0)qr[d0]=*reinterpret_cast<const bf16x8*>(&Qw[(long)r32*QP+d0*16+hi*8]);
;   float mhat=0.f,l_reg=0.f;f32x16 o[2];o[0]=f32x16{};o[1]=f32x16{};f32x16 negm=f32x16{};asm volatile("":"+v"(negm));
;     ...
;   bool resc=false;
;     ...
;   f32x16 pA0,pA1,pB0,pB1;
;   int sl_prev=0,sl_cur=0,sl_next=SLOTB;
;     ...
;   DMA_K(2,2*SLOTB);
;   WAIT_BAR(3);
;   qkt(pA0,pA1,Kbase,qr,negm,r32,hi);asm volatile("s_nop 15\n\ts_nop 7":"+v"(pA0),"+v"(pA1));CMASK(pA0,pA1,0);
.LBB0_477:
	s_mov_b64 s[4:5], -1
	s_and_b64 vcc, exec, s[0:1]
	s_cbranch_vccz .LBB0_471
	s_ashr_i32 s0, s6, 4
	s_and_b32 s1, s0, -8
	s_bfe_u32 s4, s6, 0x30004
	s_or_b32 s1, s1, s4
	s_lshr_b32 s0, s0, 29
	s_add_i32 s0, s1, s0
	s_ashr_i32 s8, s0, 3
	v_mov_b32_e32 v44, v0
	s_and_b32 s0, s0, -8
	s_ashr_i32 s9, s8, 31
	v_readfirstlane_b32 s12, v44
	s_lshl_b32 s4, s6, 8
	s_sub_i32 s13, s1, s0
	s_ashr_i32 s11, s12, 6
	s_lshl_b64 s[0:1], s[8:9], 12
	s_and_b32 s4, s4, 0xf00
	s_or_b32 s0, s0, s4
	s_lshl_b32 s4, s11, 5
	s_ashr_i32 s5, s4, 31
	s_add_u32 s0, s0, s4
	s_addc_u32 s1, s1, s5
	s_lshl_b64 s[4:5], s[0:1], 10
	s_lshl_b64 s[0:1], s[0:1], 11
	s_add_u32 s14, s30, s0
	s_addc_u32 s15, s33, s1
	s_lshl_b32 s0, s13, 6
	s_ashr_i32 s1, s0, 31
	s_lshl_b64 s[6:7], s[0:1], 1
	s_add_u32 s0, s14, s6
	s_addc_u32 s1, s15, s7
	s_lshl_b64 s[8:9], s[8:9], 21
	s_add_u32 s14, s46, s8
	s_addc_u32 s15, s47, s9
	s_lshl_b32 s8, s13, 4
	s_andn2_b32 s8, s8, 63
	s_ashr_i32 s9, s8, 31
	s_lshl_b64 s[8:9], s[8:9], 1
	v_and_b32_e32 v184, 63, v44
	s_add_u32 s8, s14, s8
	s_addc_u32 s9, s15, s9
	v_lshlrev_b32_e32 v2, 9, v184
	v_lshl_add_u64 v[4:5], s[8:9], 0, v[2:3]
	s_lshl_b32 s13, s11, 4
	v_bfe_u32 v2, v44, 2, 4
	s_lshl_b32 s14, s11, 3
	v_and_or_b32 v2, s13, 48, v2
	s_ashr_i32 s15, s14, 31
	v_lshlrev_b32_e32 v2, 9, v2
	v_lshl_add_u64 v[182:183], s[14:15], 1, v[4:5]
	v_lshl_add_u64 v[4:5], s[8:9], 0, v[2:3]
	s_ashr_i32 s8, s12, 3
	s_andn2_b32 s8, s8, 31
	s_ashr_i32 s9, s8, 31
	s_lshl_b32 s13, s11, 10
	v_readlane_b32 s20, v254, 52
	s_cmp_lg_u32 0, -1
	v_readlane_b32 s21, v254, 53
	v_lshl_add_u64 v[4:5], s[8:9], 1, v[4:5]
	s_cselect_b32 s8, 0, 0
	s_mov_b32 s21, s17
	s_add_i32 s9, s13, s8
	v_lshl_add_u64 v[84:85], v[182:183], 0, s[20:21]
	s_mov_b32 s14, m0
	s_mov_b32 m0, s9
	s_nop 0
	global_load_lds_dwordx4 v[84:85], off
	s_mov_b32 m0, s14
	v_lshlrev_b32_e32 v187, 3, v44
	s_mov_b32 s14, s20
	v_and_b32_e32 v176, 24, v187
	v_writelane_b32 v254, s14, 52
	v_lshlrev_b32_e32 v2, 1, v176
	v_lshl_add_u64 v[4:5], v[4:5], 0, v[2:3]
	v_writelane_b32 v254, s15, 53
	v_and_b32_e32 v185, 31, v44
	v_readlane_b32 s26, v254, 54
	v_lshl_add_u64 v[180:181], v[4:5], 0, s[24:25]
	v_readlane_b32 s27, v254, 55
	v_bfe_u32 v186, v44, 5, 1
	s_add_i32 s8, s9, 0x6000
	v_lshl_add_u64 v[4:5], v[180:181], 0, s[20:21]
	s_mov_b32 s14, m0
	s_mov_b32 m0, s8
	s_nop 0
	global_load_lds_dwordx4 v[4:5], off
	s_mov_b32 m0, s14
	s_mov_b32 s27, s17
	v_lshlrev_b32_e32 v2, 11, v185
	v_lshl_add_u64 v[4:5], v[182:183], 0, s[26:27]
	s_add_i32 s14, s9, 0x2000
	s_mov_b32 s15, m0
	s_mov_b32 m0, s14
	s_nop 0
	global_load_lds_dwordx4 v[4:5], off
	s_mov_b32 m0, s15
	v_lshl_or_b32 v2, v186, 4, v2
	global_load_dwordx4 v[152:155], v2, s[0:1]
	global_load_dwordx4 v[144:147], v2, s[0:1] offset:32
	global_load_dwordx4 v[136:139], v2, s[0:1] offset:64
	global_load_dwordx4 v[132:135], v2, s[0:1] offset:96
	v_lshlrev_b32_e32 v188, 10, v186
	v_lshlrev_b32_e32 v4, 4, v185
	v_add3_u32 v189, 0, v188, v4
	v_mov_b32_e32 v4, v3
	v_mov_b32_e32 v5, v3
	v_mov_b32_e32 v6, v3
	v_mov_b32_e32 v7, v3
	v_mov_b32_e32 v8, v3
	v_mov_b32_e32 v9, v3
	v_mov_b32_e32 v10, v3
	v_mov_b32_e32 v11, v3
	v_mov_b32_e32 v12, v3
	v_mov_b32_e32 v13, v3
	v_mov_b32_e32 v14, v3
	v_mov_b32_e32 v15, v3
	v_mov_b32_e32 v16, v3
	v_mov_b32_e32 v17, v3
	v_mov_b32_e32 v2, v3
	v_mov_b64_e32 v[18:19], v[16:17]
	v_mov_b64_e32 v[16:17], v[14:15]
	v_mov_b64_e32 v[14:15], v[12:13]
	v_mov_b64_e32 v[12:13], v[10:11]
	v_mov_b64_e32 v[10:11], v[8:9]
	v_mov_b64_e32 v[8:9], v[6:7]
	v_mov_b64_e32 v[6:7], v[4:5]
	v_mov_b64_e32 v[4:5], v[2:3]
	s_mov_b64 s[14:15], 0x10000
	v_lshl_add_u64 v[20:21], v[84:85], 0, s[14:15]
	s_add_i32 s14, s9, 0x4000
	s_mov_b32 s15, m0
	s_mov_b32 m0, s14
	s_nop 0
	global_load_lds_dwordx4 v[20:21], off
	s_mov_b32 m0, s15
	s_waitcnt vmcnt(3) lgkmcnt(0)
	s_barrier
	ds_read_b128 v[36:39], v189
	ds_read_b128 v[40:43], v189 offset:512
	s_waitcnt vmcnt(3) lgkmcnt(1)
	v_mfma_f32_32x32x16_bf16 v[20:35], v[36:39], v[152:155], v[4:19]
	v_lshlrev_b32_e32 v2, 1, v44
	v_and_b32_e32 v177, 32, v2
	s_mov_b64 s[20:21], 0x18000
	v_mov_b32_e32 v191, 0
	s_mov_b32 s14, -1
	s_mov_b32 s16, 0
	s_movk_i32 s22, 0x2000
	s_waitcnt lgkmcnt(0)
	v_mfma_f32_32x32x16_bf16 v[4:19], v[40:43], v[152:155], v[4:19]
	ds_read_b128 v[36:39], v189 offset:2048
	ds_read_b128 v[40:43], v189 offset:2560
	s_movk_i32 s15, 0x4000
	s_waitcnt vmcnt(2) lgkmcnt(1)
	v_mfma_f32_32x32x16_bf16 v[20:35], v[36:39], v[144:147], v[20:35]
	s_waitcnt lgkmcnt(0)
	v_mfma_f32_32x32x16_bf16 v[4:19], v[40:43], v[144:147], v[4:19]
	ds_read_b128 v[36:39], v189 offset:4096
	ds_read_b128 v[40:43], v189 offset:4608
	s_waitcnt vmcnt(1) lgkmcnt(1)
	v_mfma_f32_32x32x16_bf16 v[20:35], v[36:39], v[136:139], v[20:35]
	ds_read_b128 v[36:39], v189 offset:6144
	s_waitcnt lgkmcnt(1)
	v_mfma_f32_32x32x16_bf16 v[4:19], v[40:43], v[136:139], v[4:19]
	ds_read_b128 v[40:43], v189 offset:6656
	s_waitcnt vmcnt(0) lgkmcnt(1)
	v_mfma_f32_32x32x16_bf16 v[20:35], v[36:39], v[132:135], v[20:35]
	v_lshlrev_b32_e32 v36, 4, v44
	v_and_b32_e32 v2, 0xc0, v36
	v_lshl_or_b32 v178, v186, 8, v2
	v_add_u32_e32 v2, 0, v177
	v_add3_u32 v2, v2, v176, v178
	s_waitcnt lgkmcnt(0)
; #define WAIT_BAR(N) asm volatile("s_waitcnt vmcnt(" #N ") lgkmcnt(0)\n\ts_barrier":::"memory")
;   #define DMA_K(t,slot) glds16(ksrc+(long)(((t)+t0)&(NT-1))*KVBLK*KVP,(unsigned)__builtin_amdgcn_readfirstlane(kdst+(slot)))
;   #define DMA_V(t,slot) glds16(vsrc+(long)(((t)+t0)&(NT-1))*KVBLK*KVP,(unsigned)__builtin_amdgcn_readfirstlane(vdst+(slot)))
;   #define CMASK(P0,P1,t) do{}while(0)
;   #define START(P0,P1) do{ const float rm=rowmax(P0,P1); resc=false; \
;     { const float dl=rm; mhat=fadd_s(mhat,dl); \
;       _Pragma("unroll") for(int r=0;r<16;++r){P0[r]=fsub_s(P0[r],dl);P1[r]=fsub_s(P1[r],dl);} \
;       _Pragma("unroll") for(int r=0;r<16;++r)negm[r]=-mhat; asm volatile("":"+v"(negm)); } \
;     _Pragma("unroll") for(int r=0;r<16;++r)P0[r]=__builtin_amdgcn_exp2f(P0[r]); }while(0)
;   #define ROT() do{sl_prev=sl_cur;sl_cur=sl_next;sl_next=(sl_next==(NSLOT-1)*SLOTB)?0:sl_next+SLOTB;}while(0)
;   #define CMASK(P0,P1,t) do{}while(0)
;   #define CMASK(P0,P1,t) do{}while(0)
; template<int THRL,bool NOMAX> __device__ __forceinline__ void attn_unit(int b,int h,int qb,int t0,const bf16*Q,const bf16*__restrict__ KV,const bf16*__restrict__ GA,bf16*O,char*shm){
;     ...
;   float mhat=0.f,l_reg=0.f;f32x16 o[2];o[0]=f32x16{};o[1]=f32x16{};f32x16 negm=f32x16{};asm volatile("":"+v"(negm));
;     ...
;   bool resc=false;
;     ...
;   f32x16 pA0,pA1,pB0,pB1;
;   int sl_prev=0,sl_cur=0,sl_next=SLOTB;
;     ...
;   DMA_K(2,2*SLOTB);
;   WAIT_BAR(3);
;   qkt(pA0,pA1,Kbase,qr,negm,r32,hi);asm volatile("s_nop 15\n\ts_nop 7":"+v"(pA0),"+v"(pA1));CMASK(pA0,pA1,0);
;   START(pA0,pA1);
;   _Pragma("unroll") for(int r=0;r<16;++r)pA1[r]=__builtin_amdgcn_exp2f(pA1[r]);
;   WAIT_BAR(0);
;   DMA_K(3,0);DMA_V(1,SLOTB);
;   ROT();
;   kload8(kf,kp0+sl_cur);
;   WAIT_BAR(2);
;   s16x4 vlo[8],vhi[8]; u32x4 pw0,pw1,pw2,pw3;
	v_mfma_f32_32x32x16_bf16 v[4:19], v[40:43], v[132:135], v[4:19]
	s_nop 15
	s_nop 7
	s_nop 0
	v_max3_f32 v36, v20, v21, v4
	v_max3_f32 v37, v22, v23, v5
	s_nop 0
	v_max3_f32 v36, v36, v6, v7
	v_max3_f32 v37, v37, v26, v27
	s_nop 0
	v_max3_f32 v36, v36, v24, v25
	v_max3_f32 v37, v37, v10, v11
	s_nop 0
	v_max3_f32 v36, v36, v8, v9
	v_max3_f32 v37, v37, v30, v31
	s_nop 0
	v_max3_f32 v36, v36, v28, v29
	v_max3_f32 v37, v37, v14, v15
	s_nop 0
	v_max3_f32 v36, v36, v12, v13
	v_max3_f32 v37, v37, v34, v35
	s_nop 0
	v_max3_f32 v36, v36, v32, v33
	v_max3_f32 v37, v37, v18, v19
	s_nop 0
	v_max3_f32 v36, v36, v16, v17
	s_nop 0
	v_max_f32_e32 v36, v36, v37
	s_nop 0
	v_mov_b32_e32 v37, v36
	s_nop 1
	v_permlane32_swap_b32_e32 v36, v37
	v_max_f32_e32 v36, v36, v37
	s_nop 0
	v_add_f32_e32 v37, v3, v36
	v_sub_f32_e32 v20, v20, v36
	v_sub_f32_e32 v4, v4, v36
	v_sub_f32_e32 v21, v21, v36
	v_sub_f32_e32 v5, v5, v36
	v_sub_f32_e32 v22, v22, v36
	v_sub_f32_e32 v6, v6, v36
	v_sub_f32_e32 v23, v23, v36
	v_sub_f32_e32 v7, v7, v36
	v_sub_f32_e32 v24, v24, v36
	v_sub_f32_e32 v8, v8, v36
	v_sub_f32_e32 v25, v25, v36
	v_sub_f32_e32 v9, v9, v36
	v_sub_f32_e32 v26, v26, v36
	v_sub_f32_e32 v10, v10, v36
	v_sub_f32_e32 v27, v27, v36
	v_sub_f32_e32 v11, v11, v36
	v_sub_f32_e32 v28, v28, v36
	v_sub_f32_e32 v12, v12, v36
	v_sub_f32_e32 v29, v29, v36
	v_sub_f32_e32 v13, v13, v36
	v_sub_f32_e32 v30, v30, v36
	v_sub_f32_e32 v14, v14, v36
	v_sub_f32_e32 v31, v31, v36
	v_sub_f32_e32 v15, v15, v36
	v_sub_f32_e32 v32, v32, v36
	v_sub_f32_e32 v16, v16, v36
	v_sub_f32_e32 v33, v33, v36
	v_sub_f32_e32 v17, v17, v36
	v_sub_f32_e32 v34, v34, v36
	v_sub_f32_e32 v18, v18, v36
	v_sub_f32_e32 v35, v35, v36
	v_sub_f32_e32 v19, v19, v36
	s_nop 0
	v_xor_b32_e32 v36, 0x80000000, v37
	v_mov_b32_e32 v37, v36
	v_mov_b32_e32 v38, v36
	v_mov_b32_e32 v39, v36
	v_mov_b32_e32 v40, v36
	v_mov_b32_e32 v41, v36
	v_mov_b32_e32 v42, v36
	v_mov_b32_e32 v43, v36
	v_mov_b32_e32 v44, v36
	v_mov_b32_e32 v45, v36
	v_mov_b32_e32 v46, v36
	v_mov_b32_e32 v47, v36
	v_mov_b32_e32 v48, v36
	v_mov_b32_e32 v49, v36
	v_mov_b32_e32 v50, v36
	v_mov_b32_e32 v51, v36
	s_waitcnt vmcnt(0) lgkmcnt(0)
	s_barrier
	v_exp_f32_e32 v52, v4
	v_exp_f32_e32 v53, v5
	v_lshl_add_u64 v[4:5], v[84:85], 0, s[20:21]
	s_mov_b32 s20, m0
	s_mov_b32 m0, s9
	s_nop 0
	global_load_lds_dwordx4 v[4:5], off
	s_mov_b32 m0, s20
	s_mov_b32 s20, s26
	v_writelane_b32 v254, s20, 54
	v_lshl_add_u64 v[4:5], v[180:181], 0, s[26:27]
	v_exp_f32_e32 v68, v20
	v_writelane_b32 v254, s21, 55
	s_add_i32 s20, s9, 0x8000
	s_mov_b32 s21, m0
	s_mov_b32 m0, s20
	s_nop 0
	global_load_lds_dwordx4 v[4:5], off
	s_mov_b32 m0, s21
	ds_read_b128 v[84:87], v189 offset:8192
	ds_read_b128 v[168:171], v189 offset:8704
	ds_read_b128 v[172:175], v189 offset:10240
	ds_read_b128 v[164:167], v189 offset:10752
	ds_read_b128 v[128:131], v189 offset:12288
	ds_read_b128 v[124:127], v189 offset:12800
	ds_read_b128 v[120:123], v189 offset:14336
	ds_read_b128 v[116:119], v189 offset:14848
	v_exp_f32_e32 v69, v21
	v_exp_f32_e32 v70, v22
	v_exp_f32_e32 v71, v23
	v_exp_f32_e32 v72, v24
	v_exp_f32_e32 v73, v25
	v_exp_f32_e32 v74, v26
	v_exp_f32_e32 v75, v27
	v_exp_f32_e32 v76, v28
	v_exp_f32_e32 v77, v29
	v_exp_f32_e32 v78, v30
	v_exp_f32_e32 v79, v31
	v_exp_f32_e32 v80, v32
	v_exp_f32_e32 v81, v33
	v_exp_f32_e32 v82, v34
	v_exp_f32_e32 v83, v35
	v_exp_f32_e32 v54, v6
	v_exp_f32_e32 v55, v7
	v_exp_f32_e32 v56, v8
	v_exp_f32_e32 v57, v9
	v_exp_f32_e32 v58, v10
	v_exp_f32_e32 v59, v11
	v_exp_f32_e32 v60, v12
	v_exp_f32_e32 v61, v13
	v_exp_f32_e32 v62, v14
	v_exp_f32_e32 v63, v15
	v_exp_f32_e32 v64, v16
	v_exp_f32_e32 v65, v17
	v_exp_f32_e32 v66, v18
	v_exp_f32_e32 v67, v19
	s_waitcnt vmcnt(2) lgkmcnt(0)
	s_barrier
	v_readlane_b32 s20, v254, 35
	v_readlane_b32 s21, v254, 33
	v_mov_b32_e32 v4, 0
	v_mov_b32_e32 v5, v191
	v_mov_b32_e32 v6, v191
	v_mov_b32_e32 v7, v191
	v_mov_b32_e32 v8, v191
	v_mov_b32_e32 v9, v191
	v_mov_b32_e32 v10, v191
	v_mov_b32_e32 v11, v191
	v_mov_b32_e32 v12, v191
	v_mov_b32_e32 v13, v191
	v_mov_b32_e32 v14, v191
	v_mov_b32_e32 v15, v191
	v_mov_b32_e32 v16, v191
	v_mov_b32_e32 v17, v191
	v_mov_b32_e32 v18, v191
	v_mov_b32_e32 v19, v191
	v_mov_b32_e32 v20, 0
	v_mov_b32_e32 v21, v191
	v_mov_b32_e32 v22, v191
	v_mov_b32_e32 v23, v191
	v_mov_b32_e32 v24, v191
	v_mov_b32_e32 v25, v191
	v_mov_b32_e32 v26, v191
	v_mov_b32_e32 v27, v191
	v_mov_b32_e32 v28, v191
	v_mov_b32_e32 v29, v191
	v_mov_b32_e32 v30, v191
	v_mov_b32_e32 v31, v191
	v_mov_b32_e32 v32, v191
	v_mov_b32_e32 v33, v191
	v_mov_b32_e32 v34, v191
	v_mov_b32_e32 v35, v191
	s_cmp_lt_u32 s12, 0x100
	s_cbranch_scc1 attn_stg_m_loop
	s_waitcnt vmcnt(0)
	s_barrier
;   #define RESC() do{ if(resc){ asm volatile("s_waitcnt lgkmcnt(0)":::"memory"); \
;       _Pragma("unroll") for(int d_=0;d_<2;++d_) _Pragma("unroll") for(int r=0;r<16;++r)o[d_][r]*=wsf[crow(r,hi)]; } }while(0)
;   #define ROT() do{sl_prev=sl_cur;sl_cur=sl_next;sl_next=(sl_next==(NSLOT-1)*SLOTB)?0:sl_next+SLOTB;}while(0)
;   #define WAIT_STEADY() WAIT_BAR(3)
;   #define WAIT_STEADY() WAIT_BAR(2)
; template<int THRL,bool NOMAX> __device__ __forceinline__ void attn_unit(int b,int h,int qb,int t0,const bf16*Q,const bf16*__restrict__ KV,const bf16*__restrict__ GA,bf16*O,char*shm){
;     ...
;   int t=1;
;     ...
;   for(;t+5<NT;t+=2){
;     STEP(pB0,pB1,pA0,pA1,t,true,true,true);     WAIT_STEADY(); RESC(); ROT();
;     STEP(pA0,pA1,pB0,pB1,t+1,true,true,true);   WAIT_STEADY(); RESC(); ROT();
;   }
.LBB0_479:
	v_add_u32_e32 v179, s16, v2
	ds_read_b64_tr_b16 v[198:199], v179 offset:24576
	ds_read_b64_tr_b16 v[200:201], v179 offset:25088
	v_add_f32_e32 v88, v68, v69
	v_add_f32_e32 v88, v70, v88
	v_add_f32_e32 v88, v71, v88
	v_add_f32_e32 v88, v72, v88
	v_add_f32_e32 v88, v73, v88
	v_cvt_pk_bf16_f32 v160, v68, v69
	v_cvt_pk_bf16_f32 v161, v70, v71
	v_mfma_f32_32x32x16_bf16 v[100:115], v[84:87], v[152:155], v[36:51]
	ds_read_b64_tr_b16 v[202:203], v179 offset:28672
	ds_read_b64_tr_b16 v[204:205], v179 offset:29184
	v_add_f32_e32 v68, v74, v88
	v_mfma_f32_32x32x16_bf16 v[84:99], v[168:171], v[152:155], v[36:51]
	v_add_f32_e32 v68, v75, v68
	v_add_f32_e32 v68, v76, v68
	v_add_f32_e32 v140, v77, v68
	v_cvt_pk_bf16_f32 v162, v72, v73
	v_cvt_pk_bf16_f32 v163, v74, v75
	ds_read_b64_tr_b16 v[68:69], v179 offset:25600
	ds_read_b64_tr_b16 v[70:71], v179 offset:26112
	v_add_f32_e32 v72, v78, v140
	v_add_f32_e32 v72, v79, v72
	v_add_f32_e32 v72, v80, v72
	v_add_f32_e32 v140, v81, v72
	v_cvt_pk_bf16_f32 v156, v76, v77
	v_cvt_pk_bf16_f32 v157, v78, v79
	v_mfma_f32_32x32x16_bf16 v[100:115], v[172:175], v[144:147], v[100:115]
	ds_read_b64_tr_b16 v[72:73], v179 offset:29696
	ds_read_b64_tr_b16 v[74:75], v179 offset:30208
	v_mfma_f32_32x32x16_bf16 v[84:99], v[164:167], v[144:147], v[84:99]
	v_add_f32_e32 v76, v82, v140
	v_add_f32_e32 v76, v83, v76
	v_add_f32_e32 v76, v52, v76
	v_add_f32_e32 v140, v53, v76
	v_cvt_pk_bf16_f32 v158, v80, v81
	v_cvt_pk_bf16_f32 v159, v82, v83
	ds_read_b64_tr_b16 v[76:77], v179 offset:26624
	ds_read_b64_tr_b16 v[78:79], v179 offset:27136
	v_add_f32_e32 v80, v54, v140
	v_add_f32_e32 v80, v55, v80
	v_add_f32_e32 v80, v56, v80
	v_add_f32_e32 v80, v57, v80
	v_cvt_pk_bf16_f32 v148, v52, v53
	v_cvt_pk_bf16_f32 v149, v54, v55
	v_mfma_f32_32x32x16_bf16 v[100:115], v[128:131], v[136:139], v[100:115]
	ds_read_b64_tr_b16 v[52:53], v179 offset:30720
	ds_read_b64_tr_b16 v[54:55], v179 offset:31232
	v_mfma_f32_32x32x16_bf16 v[84:99], v[124:127], v[136:139], v[84:99]
	v_add_f32_e32 v80, v58, v80
	v_add_f32_e32 v80, v59, v80
	v_add_f32_e32 v80, v60, v80
	v_add_f32_e32 v80, v61, v80
	v_cvt_pk_bf16_f32 v150, v56, v57
	v_cvt_pk_bf16_f32 v151, v58, v59
	ds_read_b64_tr_b16 v[56:57], v179 offset:27648
	ds_read_b64_tr_b16 v[58:59], v179 offset:28160
	v_add_f32_e32 v80, v62, v80
	v_add_f32_e32 v80, v63, v80
	v_add_f32_e32 v80, v64, v80
	v_add_f32_e32 v80, v65, v80
	v_cvt_pk_bf16_f32 v140, v60, v61
	v_cvt_pk_bf16_f32 v141, v62, v63
	v_mfma_f32_32x32x16_bf16 v[100:115], v[120:123], v[132:135], v[100:115]
	ds_read_b64_tr_b16 v[60:61], v179 offset:31744
	ds_read_b64_tr_b16 v[62:63], v179 offset:32256
	v_mfma_f32_32x32x16_bf16 v[84:99], v[116:119], v[132:135], v[84:99]
	v_add_f32_e32 v80, v66, v80
	v_add_f32_e32 v80, v67, v80
	v_add_f32_e32 v179, 0, v80
	v_cvt_pk_bf16_f32 v142, v64, v65
	v_cvt_pk_bf16_f32 v143, v66, v67
	s_add_i32 s16, s20, 0xffff4000
	s_and_b32 s16, s16, 0xfc000
	s_lshl_b32 s16, s16, 1
	v_lshl_add_u64 v[220:221], v[180:181], 0, s[16:17]
	s_add_i32 m0, s15, s8
	s_nop 0
	global_load_lds_dwordx4 v[220:221], off
	s_add_i32 s16, s21, 0x4000
	s_and_b32 s16, s16, 0xfc000
	s_lshl_b32 s16, s16, 1
	v_lshl_add_u64 v[218:219], v[182:183], 0, s[16:17]
	s_add_i32 m0, s22, s9
	s_nop 0
	global_load_lds_dwordx4 v[218:219], off
	s_waitcnt lgkmcnt(4)
	v_mfma_f32_32x32x16_bf16 v[4:19], v[160:163], v[198:201], v[4:19]
	v_exp_f32_e32 v100, v100
	v_exp_f32_e32 v101, v101
	v_exp_f32_e32 v102, v102
	v_exp_f32_e32 v103, v103
	v_mfma_f32_32x32x16_bf16 v[20:35], v[160:163], v[202:205], v[20:35]
	v_exp_f32_e32 v104, v104
	v_exp_f32_e32 v105, v105
	v_exp_f32_e32 v106, v106
	v_exp_f32_e32 v107, v107
	v_add_u32_e32 v80, s15, v189
	ds_read_b128 v[64:67], v80
	ds_read_b128 v[120:123], v80 offset:512
	v_mfma_f32_32x32x16_bf16 v[4:19], v[156:159], v[68:71], v[4:19]
	v_exp_f32_e32 v108, v108
	v_exp_f32_e32 v109, v109
	v_exp_f32_e32 v110, v110
	v_exp_f32_e32 v111, v111
	ds_read_b128 v[124:127], v80 offset:2048
	ds_read_b128 v[128:131], v80 offset:2560
	v_mfma_f32_32x32x16_bf16 v[20:35], v[156:159], v[72:75], v[20:35]
	v_exp_f32_e32 v112, v112
	v_exp_f32_e32 v113, v113
	v_exp_f32_e32 v114, v114
	v_exp_f32_e32 v115, v115
	ds_read_b128 v[164:167], v80 offset:4096
	ds_read_b128 v[168:171], v80 offset:4608
	v_mfma_f32_32x32x16_bf16 v[4:19], v[148:151], v[76:79], v[4:19]
	v_exp_f32_e32 v84, v84
	v_exp_f32_e32 v85, v85
	v_exp_f32_e32 v86, v86
	v_exp_f32_e32 v87, v87
	ds_read_b128 v[172:175], v80 offset:6144
	ds_read_b128 v[116:119], v80 offset:6656
	v_mfma_f32_32x32x16_bf16 v[20:35], v[148:151], v[52:55], v[20:35]
	v_exp_f32_e32 v88, v88
	v_exp_f32_e32 v89, v89
	v_exp_f32_e32 v90, v90
	v_exp_f32_e32 v91, v91
	s_waitcnt lgkmcnt(8)
	v_mfma_f32_32x32x16_bf16 v[4:19], v[140:143], v[56:59], v[4:19]
	v_exp_f32_e32 v92, v92
	v_exp_f32_e32 v93, v93
	v_exp_f32_e32 v94, v94
	v_exp_f32_e32 v95, v95
	v_mfma_f32_32x32x16_bf16 v[20:35], v[140:143], v[60:63], v[20:35]
	v_exp_f32_e32 v96, v96
	v_exp_f32_e32 v97, v97
	v_exp_f32_e32 v98, v98
	v_exp_f32_e32 v99, v99
	s_waitcnt vmcnt(1) lgkmcnt(0)
	s_barrier
;   #define RESC() do{ if(resc){ asm volatile("s_waitcnt lgkmcnt(0)":::"memory"); \
;       _Pragma("unroll") for(int d_=0;d_<2;++d_) _Pragma("unroll") for(int r=0;r<16;++r)o[d_][r]*=wsf[crow(r,hi)]; } }while(0)
;   #define ROT() do{sl_prev=sl_cur;sl_cur=sl_next;sl_next=(sl_next==(NSLOT-1)*SLOTB)?0:sl_next+SLOTB;}while(0)
;   #define WAIT_STEADY() WAIT_BAR(3)
;   #define WAIT_STEADY() WAIT_BAR(2)
; template<int THRL,bool NOMAX> __device__ __forceinline__ void attn_unit(int b,int h,int qb,int t0,const bf16*Q,const bf16*__restrict__ KV,const bf16*__restrict__ GA,bf16*O,char*shm){
;     ...
;   int t=1;
;     ...
;   for(;t+5<NT;t+=2){
;     STEP(pB0,pB1,pA0,pA1,t,true,true,true);     WAIT_STEADY(); RESC(); ROT();
;     STEP(pA0,pA1,pB0,pB1,t+1,true,true,true);   WAIT_STEADY(); RESC(); ROT();
;   }
	s_add_i32 s16, s15, 0x2000
	s_cmpk_lg_i32 s15, 0x4000
	s_cselect_b32 s23, s16, 0
	v_add_u32_e32 v190, s22, v2
	ds_read_b64_tr_b16 v[198:199], v190 offset:24576
	ds_read_b64_tr_b16 v[200:201], v190 offset:25088
	v_mfma_f32_32x32x16_bf16 v[68:83], v[64:67], v[152:155], v[36:51]
	v_add_f32_e32 v52, v100, v101
	v_add_f32_e32 v52, v102, v52
	v_add_f32_e32 v52, v103, v52
	v_add_f32_e32 v52, v104, v52
	v_add_f32_e32 v52, v105, v52
	v_cvt_pk_bf16_f32 v160, v100, v101
	v_cvt_pk_bf16_f32 v161, v102, v103
	ds_read_b64_tr_b16 v[202:203], v190 offset:28672
	ds_read_b64_tr_b16 v[204:205], v190 offset:29184
	v_add_f32_e32 v52, v106, v52
	v_add_f32_e32 v52, v107, v52
	v_add_f32_e32 v52, v108, v52
	v_add_f32_e32 v140, v109, v52
	v_mfma_f32_32x32x16_bf16 v[52:67], v[120:123], v[152:155], v[36:51]
	v_cvt_pk_bf16_f32 v162, v104, v105
	v_cvt_pk_bf16_f32 v163, v106, v107
	ds_read_b64_tr_b16 v[100:101], v190 offset:25600
	ds_read_b64_tr_b16 v[102:103], v190 offset:26112
	v_mfma_f32_32x32x16_bf16 v[68:83], v[124:127], v[144:147], v[68:83]
	v_add_f32_e32 v104, v110, v140
	v_add_f32_e32 v104, v111, v104
	v_add_f32_e32 v104, v112, v104
	v_add_f32_e32 v120, v113, v104
	v_cvt_pk_bf16_f32 v156, v108, v109
	v_cvt_pk_bf16_f32 v157, v110, v111
	ds_read_b64_tr_b16 v[104:105], v190 offset:29696
	ds_read_b64_tr_b16 v[106:107], v190 offset:30208
	v_mfma_f32_32x32x16_bf16 v[52:67], v[128:131], v[144:147], v[52:67]
	v_add_f32_e32 v108, v114, v120
	v_add_f32_e32 v108, v115, v108
	v_add_f32_e32 v108, v84, v108
	v_add_f32_e32 v120, v85, v108
	v_cvt_pk_bf16_f32 v158, v112, v113
	v_cvt_pk_bf16_f32 v159, v114, v115
	ds_read_b64_tr_b16 v[108:109], v190 offset:26624
	ds_read_b64_tr_b16 v[110:111], v190 offset:27136
	v_mfma_f32_32x32x16_bf16 v[68:83], v[164:167], v[136:139], v[68:83]
	v_add_f32_e32 v112, v86, v120
	v_add_f32_e32 v112, v87, v112
	v_add_f32_e32 v112, v88, v112
	v_add_f32_e32 v120, v89, v112
	v_cvt_pk_bf16_f32 v148, v84, v85
	v_cvt_pk_bf16_f32 v149, v86, v87
	ds_read_b64_tr_b16 v[112:113], v190 offset:30720
	ds_read_b64_tr_b16 v[114:115], v190 offset:31232
	v_mfma_f32_32x32x16_bf16 v[52:67], v[168:171], v[136:139], v[52:67]
	v_add_f32_e32 v84, v90, v120
	v_add_f32_e32 v84, v91, v84
	v_add_f32_e32 v84, v92, v84
	v_add_f32_e32 v84, v93, v84
	v_cvt_pk_bf16_f32 v150, v88, v89
	v_cvt_pk_bf16_f32 v151, v90, v91
	ds_read_b64_tr_b16 v[88:89], v190 offset:27648
	ds_read_b64_tr_b16 v[90:91], v190 offset:28160
	v_mfma_f32_32x32x16_bf16 v[68:83], v[172:175], v[132:135], v[68:83]
	v_add_f32_e32 v84, v94, v84
	v_add_f32_e32 v84, v95, v84
	v_add_f32_e32 v84, v96, v84
	v_add_f32_e32 v84, v97, v84
	v_cvt_pk_bf16_f32 v140, v92, v93
	v_cvt_pk_bf16_f32 v141, v94, v95
	ds_read_b64_tr_b16 v[92:93], v190 offset:31744
	ds_read_b64_tr_b16 v[94:95], v190 offset:32256
	v_mfma_f32_32x32x16_bf16 v[52:67], v[116:119], v[132:135], v[52:67]
	v_add_f32_e32 v84, v98, v84
	v_add_f32_e32 v84, v99, v84
	v_add_f32_e32 v190, 0, v84
	v_cvt_pk_bf16_f32 v142, v96, v97
	v_cvt_pk_bf16_f32 v143, v98, v99
	s_and_b32 s16, s21, 0xfc000
	s_lshl_b32 s16, s16, 1
	v_lshl_add_u64 v[220:221], v[180:181], 0, s[16:17]
	s_add_i32 m0, s23, s8
	s_nop 0
	global_load_lds_dwordx4 v[220:221], off
	s_and_b32 s16, s20, 0xfc000
	s_lshl_b32 s16, s16, 1
	v_lshl_add_u64 v[218:219], v[182:183], 0, s[16:17]
	s_add_i32 m0, s15, s9
	s_nop 0
	global_load_lds_dwordx4 v[218:219], off
	s_waitcnt lgkmcnt(4)
	v_mfma_f32_32x32x16_bf16 v[4:19], v[160:163], v[198:201], v[4:19]
	v_exp_f32_e32 v68, v68
	v_exp_f32_e32 v69, v69
	v_exp_f32_e32 v70, v70
	v_exp_f32_e32 v71, v71
	v_mfma_f32_32x32x16_bf16 v[20:35], v[160:163], v[202:205], v[20:35]
	v_exp_f32_e32 v72, v72
	v_exp_f32_e32 v73, v73
	v_exp_f32_e32 v74, v74
	v_exp_f32_e32 v75, v75
	v_add_u32_e32 v96, s23, v189
	ds_read_b128 v[84:87], v96
	ds_read_b128 v[168:171], v96 offset:512
	v_mfma_f32_32x32x16_bf16 v[4:19], v[156:159], v[100:103], v[4:19]
	v_exp_f32_e32 v76, v76
	v_exp_f32_e32 v77, v77
	v_exp_f32_e32 v78, v78
	v_exp_f32_e32 v79, v79
	ds_read_b128 v[172:175], v96 offset:2048
	ds_read_b128 v[164:167], v96 offset:2560
	v_mfma_f32_32x32x16_bf16 v[20:35], v[156:159], v[104:107], v[20:35]
	v_exp_f32_e32 v80, v80
	v_exp_f32_e32 v81, v81
	v_exp_f32_e32 v82, v82
	v_exp_f32_e32 v83, v83
	ds_read_b128 v[128:131], v96 offset:4096
	ds_read_b128 v[124:127], v96 offset:4608
	v_mfma_f32_32x32x16_bf16 v[4:19], v[148:151], v[108:111], v[4:19]
	v_exp_f32_e32 v52, v52
	v_exp_f32_e32 v53, v53
	v_exp_f32_e32 v54, v54
	v_exp_f32_e32 v55, v55
	ds_read_b128 v[120:123], v96 offset:6144
	ds_read_b128 v[116:119], v96 offset:6656
	v_mfma_f32_32x32x16_bf16 v[20:35], v[148:151], v[112:115], v[20:35]
	v_exp_f32_e32 v56, v56
	v_exp_f32_e32 v57, v57
	v_exp_f32_e32 v58, v58
	v_exp_f32_e32 v59, v59
	s_waitcnt lgkmcnt(8)
	v_mfma_f32_32x32x16_bf16 v[4:19], v[140:143], v[88:91], v[4:19]
	v_exp_f32_e32 v60, v60
	v_exp_f32_e32 v61, v61
	v_exp_f32_e32 v62, v62
	v_exp_f32_e32 v63, v63
	v_mfma_f32_32x32x16_bf16 v[20:35], v[140:143], v[92:95], v[20:35]
	v_exp_f32_e32 v64, v64
	v_exp_f32_e32 v65, v65
	v_exp_f32_e32 v66, v66
	v_exp_f32_e32 v67, v67
	s_add_i32 s26, s23, 0x2000
	s_waitcnt vmcnt(1) lgkmcnt(0)
	s_barrier
	s_cmpk_lg_i32 s23, 0x4000
	v_add_f32_e32 v88, v191, v179
	s_mov_b32 s16, s15
	s_cselect_b32 s15, s26, 0
	s_add_i32 s14, s14, 2
	s_add_i32 s21, s21, 0x8000
	s_add_i32 s20, s20, 0x8000
	s_mov_b32 s22, s23
	v_add_f32_e32 v191, v88, v190
	s_cmp_gt_u32 s14, 56
	s_cbranch_scc0 .LBB0_479
	s_branch attn_stg_join
;   #define RESC() do{ if(resc){ asm volatile("s_waitcnt lgkmcnt(0)":::"memory"); \
;       _Pragma("unroll") for(int d_=0;d_<2;++d_) _Pragma("unroll") for(int r=0;r<16;++r)o[d_][r]*=wsf[crow(r,hi)]; } }while(0)
;   #define ROT() do{sl_prev=sl_cur;sl_cur=sl_next;sl_next=(sl_next==(NSLOT-1)*SLOTB)?0:sl_next+SLOTB;}while(0)
;   #define WAIT_STEADY() WAIT_BAR(3)
;   #define WAIT_STEADY() WAIT_BAR(2)
; template<int THRL,bool NOMAX> __device__ __forceinline__ void attn_unit(int b,int h,int qb,int t0,const bf16*Q,const bf16*__restrict__ KV,const bf16*__restrict__ GA,bf16*O,char*shm){
;     ...
;   int t=1;
;     ...
;   for(;t+5<NT;t+=2){
;     STEP(pB0,pB1,pA0,pA1,t,true,true,true);     WAIT_STEADY(); RESC(); ROT();
;     STEP(pA0,pA1,pB0,pB1,t+1,true,true,true);   WAIT_STEADY(); RESC(); ROT();
;   }
attn_stg_m_loop:
	v_add_u32_e32 v179, s16, v2
	ds_read_b64_tr_b16 v[198:199], v179 offset:24576
	ds_read_b64_tr_b16 v[200:201], v179 offset:25088
	v_add_f32_e32 v88, v68, v69
	v_add_f32_e32 v88, v70, v88
	v_add_f32_e32 v88, v71, v88
	v_add_f32_e32 v88, v72, v88
	v_add_f32_e32 v88, v73, v88
	v_cvt_pk_bf16_f32 v160, v68, v69
	v_cvt_pk_bf16_f32 v161, v70, v71
	v_mfma_f32_32x32x16_bf16 v[100:115], v[84:87], v[152:155], v[36:51]
	ds_read_b64_tr_b16 v[202:203], v179 offset:28672
	ds_read_b64_tr_b16 v[204:205], v179 offset:29184
	v_add_f32_e32 v68, v74, v88
	v_mfma_f32_32x32x16_bf16 v[84:99], v[168:171], v[152:155], v[36:51]
	v_add_f32_e32 v68, v75, v68
	v_add_f32_e32 v68, v76, v68
	v_add_f32_e32 v140, v77, v68
	v_cvt_pk_bf16_f32 v162, v72, v73
	v_cvt_pk_bf16_f32 v163, v74, v75
	ds_read_b64_tr_b16 v[68:69], v179 offset:25600
	ds_read_b64_tr_b16 v[70:71], v179 offset:26112
	v_add_f32_e32 v72, v78, v140
	v_add_f32_e32 v72, v79, v72
	v_add_f32_e32 v72, v80, v72
	v_add_f32_e32 v140, v81, v72
	v_cvt_pk_bf16_f32 v156, v76, v77
	v_cvt_pk_bf16_f32 v157, v78, v79
	v_mfma_f32_32x32x16_bf16 v[100:115], v[172:175], v[144:147], v[100:115]
	ds_read_b64_tr_b16 v[72:73], v179 offset:29696
	ds_read_b64_tr_b16 v[74:75], v179 offset:30208
	v_mfma_f32_32x32x16_bf16 v[84:99], v[164:167], v[144:147], v[84:99]
	v_add_f32_e32 v76, v82, v140
	v_add_f32_e32 v76, v83, v76
	v_add_f32_e32 v76, v52, v76
	v_add_f32_e32 v140, v53, v76
	v_cvt_pk_bf16_f32 v158, v80, v81
	v_cvt_pk_bf16_f32 v159, v82, v83
	ds_read_b64_tr_b16 v[76:77], v179 offset:26624
	ds_read_b64_tr_b16 v[78:79], v179 offset:27136
	v_add_f32_e32 v80, v54, v140
	v_add_f32_e32 v80, v55, v80
	v_add_f32_e32 v80, v56, v80
	v_add_f32_e32 v80, v57, v80
	v_cvt_pk_bf16_f32 v148, v52, v53
	v_cvt_pk_bf16_f32 v149, v54, v55
	v_mfma_f32_32x32x16_bf16 v[100:115], v[128:131], v[136:139], v[100:115]
	ds_read_b64_tr_b16 v[52:53], v179 offset:30720
	ds_read_b64_tr_b16 v[54:55], v179 offset:31232
	v_mfma_f32_32x32x16_bf16 v[84:99], v[124:127], v[136:139], v[84:99]
	v_add_f32_e32 v80, v58, v80
	v_add_f32_e32 v80, v59, v80
	v_add_f32_e32 v80, v60, v80
	v_add_f32_e32 v80, v61, v80
	v_cvt_pk_bf16_f32 v150, v56, v57
	v_cvt_pk_bf16_f32 v151, v58, v59
	ds_read_b64_tr_b16 v[56:57], v179 offset:27648
	ds_read_b64_tr_b16 v[58:59], v179 offset:28160
	v_add_f32_e32 v80, v62, v80
	v_add_f32_e32 v80, v63, v80
	v_add_f32_e32 v80, v64, v80
	v_add_f32_e32 v80, v65, v80
	v_cvt_pk_bf16_f32 v140, v60, v61
	v_cvt_pk_bf16_f32 v141, v62, v63
	v_mfma_f32_32x32x16_bf16 v[100:115], v[120:123], v[132:135], v[100:115]
	ds_read_b64_tr_b16 v[60:61], v179 offset:31744
	ds_read_b64_tr_b16 v[62:63], v179 offset:32256
	v_mfma_f32_32x32x16_bf16 v[84:99], v[116:119], v[132:135], v[84:99]
	v_add_f32_e32 v80, v66, v80
	v_add_f32_e32 v80, v67, v80
	v_add_f32_e32 v179, 0, v80
	v_cvt_pk_bf16_f32 v142, v64, v65
	v_cvt_pk_bf16_f32 v143, v66, v67
	s_waitcnt vmcnt(0)
	s_barrier
	s_add_i32 s16, s21, 0x4000
	s_and_b32 s16, s16, 0xfc000
	s_lshl_b32 s16, s16, 1
	v_lshl_add_u64 v[218:219], v[182:183], 0, s[16:17]
	s_add_i32 m0, s22, s9
	s_nop 0
	global_load_lds_dwordx4 v[218:219], off
	s_add_i32 s16, s20, 0xffff4000
	s_and_b32 s16, s16, 0xfc000
	s_lshl_b32 s16, s16, 1
	v_lshl_add_u64 v[220:221], v[180:181], 0, s[16:17]
	s_add_i32 m0, s15, s8
	s_nop 0
	global_load_lds_dwordx4 v[220:221], off
	s_waitcnt lgkmcnt(4)
	v_mfma_f32_32x32x16_bf16 v[4:19], v[160:163], v[198:201], v[4:19]
	v_exp_f32_e32 v100, v100
	v_exp_f32_e32 v101, v101
	v_exp_f32_e32 v102, v102
	v_exp_f32_e32 v103, v103
	v_mfma_f32_32x32x16_bf16 v[20:35], v[160:163], v[202:205], v[20:35]
	v_exp_f32_e32 v104, v104
	v_exp_f32_e32 v105, v105
	v_exp_f32_e32 v106, v106
	v_exp_f32_e32 v107, v107
	v_add_u32_e32 v80, s15, v189
	ds_read_b128 v[64:67], v80
	ds_read_b128 v[120:123], v80 offset:512
	v_mfma_f32_32x32x16_bf16 v[4:19], v[156:159], v[68:71], v[4:19]
	v_exp_f32_e32 v108, v108
	v_exp_f32_e32 v109, v109
	v_exp_f32_e32 v110, v110
	v_exp_f32_e32 v111, v111
	ds_read_b128 v[124:127], v80 offset:2048
	ds_read_b128 v[128:131], v80 offset:2560
	v_mfma_f32_32x32x16_bf16 v[20:35], v[156:159], v[72:75], v[20:35]
	v_exp_f32_e32 v112, v112
	v_exp_f32_e32 v113, v113
	v_exp_f32_e32 v114, v114
	v_exp_f32_e32 v115, v115
	ds_read_b128 v[164:167], v80 offset:4096
	ds_read_b128 v[168:171], v80 offset:4608
	v_mfma_f32_32x32x16_bf16 v[4:19], v[148:151], v[76:79], v[4:19]
	v_exp_f32_e32 v84, v84
	v_exp_f32_e32 v85, v85
	v_exp_f32_e32 v86, v86
	v_exp_f32_e32 v87, v87
	ds_read_b128 v[172:175], v80 offset:6144
	ds_read_b128 v[116:119], v80 offset:6656
	v_mfma_f32_32x32x16_bf16 v[20:35], v[148:151], v[52:55], v[20:35]
	v_exp_f32_e32 v88, v88
	v_exp_f32_e32 v89, v89
	v_exp_f32_e32 v90, v90
	v_exp_f32_e32 v91, v91
	s_waitcnt lgkmcnt(8)
	v_mfma_f32_32x32x16_bf16 v[4:19], v[140:143], v[56:59], v[4:19]
	v_exp_f32_e32 v92, v92
	v_exp_f32_e32 v93, v93
	v_exp_f32_e32 v94, v94
	v_exp_f32_e32 v95, v95
	v_mfma_f32_32x32x16_bf16 v[20:35], v[140:143], v[60:63], v[20:35]
	v_exp_f32_e32 v96, v96
	v_exp_f32_e32 v97, v97
	v_exp_f32_e32 v98, v98
	v_exp_f32_e32 v99, v99
	s_waitcnt lgkmcnt(0)
;   #define RESC() do{ if(resc){ asm volatile("s_waitcnt lgkmcnt(0)":::"memory"); \
;       _Pragma("unroll") for(int d_=0;d_<2;++d_) _Pragma("unroll") for(int r=0;r<16;++r)o[d_][r]*=wsf[crow(r,hi)]; } }while(0)
;   #define ROT() do{sl_prev=sl_cur;sl_cur=sl_next;sl_next=(sl_next==(NSLOT-1)*SLOTB)?0:sl_next+SLOTB;}while(0)
;   #define WAIT_STEADY() WAIT_BAR(3)
;   #define WAIT_STEADY() WAIT_BAR(2)
; template<int THRL,bool NOMAX> __device__ __forceinline__ void attn_unit(int b,int h,int qb,int t0,const bf16*Q,const bf16*__restrict__ KV,const bf16*__restrict__ GA,bf16*O,char*shm){
;     ...
;   int t=1;
;     ...
;   for(;t+5<NT;t+=2){
;     STEP(pB0,pB1,pA0,pA1,t,true,true,true);     WAIT_STEADY(); RESC(); ROT();
;     STEP(pA0,pA1,pB0,pB1,t+1,true,true,true);   WAIT_STEADY(); RESC(); ROT();
;   }
	s_add_i32 s16, s15, 0x2000
	s_cmpk_lg_i32 s15, 0x4000
	s_cselect_b32 s23, s16, 0
	v_add_u32_e32 v190, s22, v2
	ds_read_b64_tr_b16 v[198:199], v190 offset:24576
	ds_read_b64_tr_b16 v[200:201], v190 offset:25088
	v_mfma_f32_32x32x16_bf16 v[68:83], v[64:67], v[152:155], v[36:51]
	v_add_f32_e32 v52, v100, v101
	v_add_f32_e32 v52, v102, v52
	v_add_f32_e32 v52, v103, v52
	v_add_f32_e32 v52, v104, v52
	v_add_f32_e32 v52, v105, v52
	v_cvt_pk_bf16_f32 v160, v100, v101
	v_cvt_pk_bf16_f32 v161, v102, v103
	ds_read_b64_tr_b16 v[202:203], v190 offset:28672
	ds_read_b64_tr_b16 v[204:205], v190 offset:29184
	v_add_f32_e32 v52, v106, v52
	v_add_f32_e32 v52, v107, v52
	v_add_f32_e32 v52, v108, v52
	v_add_f32_e32 v140, v109, v52
	v_mfma_f32_32x32x16_bf16 v[52:67], v[120:123], v[152:155], v[36:51]
	v_cvt_pk_bf16_f32 v162, v104, v105
	v_cvt_pk_bf16_f32 v163, v106, v107
	ds_read_b64_tr_b16 v[100:101], v190 offset:25600
	ds_read_b64_tr_b16 v[102:103], v190 offset:26112
	v_mfma_f32_32x32x16_bf16 v[68:83], v[124:127], v[144:147], v[68:83]
	v_add_f32_e32 v104, v110, v140
	v_add_f32_e32 v104, v111, v104
	v_add_f32_e32 v104, v112, v104
	v_add_f32_e32 v120, v113, v104
	v_cvt_pk_bf16_f32 v156, v108, v109
	v_cvt_pk_bf16_f32 v157, v110, v111
	ds_read_b64_tr_b16 v[104:105], v190 offset:29696
	ds_read_b64_tr_b16 v[106:107], v190 offset:30208
	v_mfma_f32_32x32x16_bf16 v[52:67], v[128:131], v[144:147], v[52:67]
	v_add_f32_e32 v108, v114, v120
	v_add_f32_e32 v108, v115, v108
	v_add_f32_e32 v108, v84, v108
	v_add_f32_e32 v120, v85, v108
	v_cvt_pk_bf16_f32 v158, v112, v113
	v_cvt_pk_bf16_f32 v159, v114, v115
	ds_read_b64_tr_b16 v[108:109], v190 offset:26624
	ds_read_b64_tr_b16 v[110:111], v190 offset:27136
	v_mfma_f32_32x32x16_bf16 v[68:83], v[164:167], v[136:139], v[68:83]
	v_add_f32_e32 v112, v86, v120
	v_add_f32_e32 v112, v87, v112
	v_add_f32_e32 v112, v88, v112
	v_add_f32_e32 v120, v89, v112
	v_cvt_pk_bf16_f32 v148, v84, v85
	v_cvt_pk_bf16_f32 v149, v86, v87
	ds_read_b64_tr_b16 v[112:113], v190 offset:30720
	ds_read_b64_tr_b16 v[114:115], v190 offset:31232
	v_mfma_f32_32x32x16_bf16 v[52:67], v[168:171], v[136:139], v[52:67]
	v_add_f32_e32 v84, v90, v120
	v_add_f32_e32 v84, v91, v84
	v_add_f32_e32 v84, v92, v84
	v_add_f32_e32 v84, v93, v84
	v_cvt_pk_bf16_f32 v150, v88, v89
	v_cvt_pk_bf16_f32 v151, v90, v91
	ds_read_b64_tr_b16 v[88:89], v190 offset:27648
	ds_read_b64_tr_b16 v[90:91], v190 offset:28160
	v_mfma_f32_32x32x16_bf16 v[68:83], v[172:175], v[132:135], v[68:83]
	v_add_f32_e32 v84, v94, v84
	v_add_f32_e32 v84, v95, v84
	v_add_f32_e32 v84, v96, v84
	v_add_f32_e32 v84, v97, v84
	v_cvt_pk_bf16_f32 v140, v92, v93
	v_cvt_pk_bf16_f32 v141, v94, v95
	ds_read_b64_tr_b16 v[92:93], v190 offset:31744
	ds_read_b64_tr_b16 v[94:95], v190 offset:32256
	v_mfma_f32_32x32x16_bf16 v[52:67], v[116:119], v[132:135], v[52:67]
	v_add_f32_e32 v84, v98, v84
	v_add_f32_e32 v84, v99, v84
	v_add_f32_e32 v190, 0, v84
	v_cvt_pk_bf16_f32 v142, v96, v97
	v_cvt_pk_bf16_f32 v143, v98, v99
	s_waitcnt vmcnt(0)
	s_barrier
	s_and_b32 s16, s20, 0xfc000
	s_lshl_b32 s16, s16, 1
	v_lshl_add_u64 v[218:219], v[182:183], 0, s[16:17]
	s_add_i32 m0, s15, s9
	s_nop 0
	global_load_lds_dwordx4 v[218:219], off
	s_and_b32 s16, s21, 0xfc000
	s_lshl_b32 s16, s16, 1
	v_lshl_add_u64 v[220:221], v[180:181], 0, s[16:17]
	s_add_i32 m0, s23, s8
	s_nop 0
	global_load_lds_dwordx4 v[220:221], off
	s_waitcnt lgkmcnt(4)
	v_mfma_f32_32x32x16_bf16 v[4:19], v[160:163], v[198:201], v[4:19]
	v_exp_f32_e32 v68, v68
	v_exp_f32_e32 v69, v69
	v_exp_f32_e32 v70, v70
	v_exp_f32_e32 v71, v71
	v_mfma_f32_32x32x16_bf16 v[20:35], v[160:163], v[202:205], v[20:35]
	v_exp_f32_e32 v72, v72
	v_exp_f32_e32 v73, v73
	v_exp_f32_e32 v74, v74
	v_exp_f32_e32 v75, v75
	v_add_u32_e32 v96, s23, v189
	ds_read_b128 v[84:87], v96
	ds_read_b128 v[168:171], v96 offset:512
	v_mfma_f32_32x32x16_bf16 v[4:19], v[156:159], v[100:103], v[4:19]
	v_exp_f32_e32 v76, v76
	v_exp_f32_e32 v77, v77
	v_exp_f32_e32 v78, v78
	v_exp_f32_e32 v79, v79
	ds_read_b128 v[172:175], v96 offset:2048
	ds_read_b128 v[164:167], v96 offset:2560
	v_mfma_f32_32x32x16_bf16 v[20:35], v[156:159], v[104:107], v[20:35]
	v_exp_f32_e32 v80, v80
	v_exp_f32_e32 v81, v81
	v_exp_f32_e32 v82, v82
	v_exp_f32_e32 v83, v83
	ds_read_b128 v[128:131], v96 offset:4096
	ds_read_b128 v[124:127], v96 offset:4608
	v_mfma_f32_32x32x16_bf16 v[4:19], v[148:151], v[108:111], v[4:19]
	v_exp_f32_e32 v52, v52
	v_exp_f32_e32 v53, v53
	v_exp_f32_e32 v54, v54
	v_exp_f32_e32 v55, v55
	ds_read_b128 v[120:123], v96 offset:6144
	ds_read_b128 v[116:119], v96 offset:6656
	v_mfma_f32_32x32x16_bf16 v[20:35], v[148:151], v[112:115], v[20:35]
	v_exp_f32_e32 v56, v56
	v_exp_f32_e32 v57, v57
	v_exp_f32_e32 v58, v58
	v_exp_f32_e32 v59, v59
	s_waitcnt lgkmcnt(8)
	v_mfma_f32_32x32x16_bf16 v[4:19], v[140:143], v[88:91], v[4:19]
	v_exp_f32_e32 v60, v60
	v_exp_f32_e32 v61, v61
	v_exp_f32_e32 v62, v62
	v_exp_f32_e32 v63, v63
	v_mfma_f32_32x32x16_bf16 v[20:35], v[140:143], v[92:95], v[20:35]
	v_exp_f32_e32 v64, v64
	v_exp_f32_e32 v65, v65
	v_exp_f32_e32 v66, v66
	v_exp_f32_e32 v67, v67
	s_add_i32 s26, s23, 0x2000
	s_waitcnt lgkmcnt(0)
	s_cmpk_lg_i32 s23, 0x4000
	v_add_f32_e32 v88, v191, v179
	s_mov_b32 s16, s15
	s_cselect_b32 s15, s26, 0
	s_add_i32 s14, s14, 2
	s_add_i32 s21, s21, 0x8000
	s_add_i32 s20, s20, 0x8000
	s_mov_b32 s22, s23
	v_add_f32_e32 v191, v88, v190
	s_cmp_gt_u32 s14, 56
	s_cbranch_scc0 attn_stg_m_loop
	s_waitcnt vmcnt(0) lgkmcnt(0)
	s_barrier
;   #define RESC() do{ if(resc){ asm volatile("s_waitcnt lgkmcnt(0)":::"memory"); \
;       _Pragma("unroll") for(int d_=0;d_<2;++d_) _Pragma("unroll") for(int r=0;r<16;++r)o[d_][r]*=wsf[crow(r,hi)]; } }while(0)
;   #define ROT() do{sl_prev=sl_cur;sl_cur=sl_next;sl_next=(sl_next==(NSLOT-1)*SLOTB)?0:sl_next+SLOTB;}while(0)
;   #define ENDW(tt) do{ if((tt)+3<NT){WAIT_BAR(2);} else if((tt)+2<NT){WAIT_BAR(1);} else {WAIT_BAR(0);} }while(0)
; template<int THRL,bool NOMAX> __device__ __forceinline__ void attn_unit(int b,int h,int qb,int t0,const bf16*Q,const bf16*__restrict__ KV,const bf16*__restrict__ GA,bf16*O,char*shm){
;     ...
;   for(;t+1<NT;t+=2){
;     STEP(pB0,pB1,pA0,pA1,t,(t+3<NT),(t+1<NT),(t+1<NT));       ENDW(t);   RESC(); ROT();
;     STEP(pA0,pA1,pB0,pB1,t+1,(t+4<NT),(t+2<NT),(t+2<NT));     ENDW(t+1); RESC(); ROT();
attn_stg_join:
	s_and_b32 s12, s12, 0x3fffffc0
	s_cmp_lg_u32 0, -1
	s_cselect_b32 s14, 0, 0
	s_add_i32 s15, s14, 0x6000
	s_lshl_b32 s12, s12, 2
	v_add_u32_e32 v88, s15, v177
	s_add_i32 s12, s12, 0
	v_add3_u32 v190, v88, v176, v178
	ds_read_b64_tr_b16 v[198:199], v2 offset:32768
	ds_read_b64_tr_b16 v[200:201], v2 offset:33280
	v_add_f32_e32 v88, v68, v69
	v_add_f32_e32 v88, v70, v88
	v_add_f32_e32 v88, v71, v88
	v_add_f32_e32 v88, v72, v88
	v_add_f32_e32 v88, v73, v88
	v_cvt_pk_bf16_f32 v160, v68, v69
	v_cvt_pk_bf16_f32 v161, v70, v71
	s_waitcnt lgkmcnt(9)
	v_mfma_f32_32x32x16_bf16 v[100:115], v[84:87], v[152:155], v[36:51]
	ds_read_b64_tr_b16 v[176:177], v2 offset:36864
	ds_read_b64_tr_b16 v[178:179], v2 offset:37376
	v_add_f32_e32 v68, v74, v88
	v_add_f32_e32 v68, v75, v68
	v_add_f32_e32 v68, v76, v68
	v_add_f32_e32 v140, v77, v68
	v_cvt_pk_bf16_f32 v162, v72, v73
	v_cvt_pk_bf16_f32 v163, v74, v75
	s_waitcnt lgkmcnt(10)
	v_mfma_f32_32x32x16_bf16 v[84:99], v[168:171], v[152:155], v[36:51]
	ds_read_b64_tr_b16 v[68:69], v2 offset:33792
	ds_read_b64_tr_b16 v[70:71], v2 offset:34304
	v_add_f32_e32 v72, v78, v140
	v_add_f32_e32 v72, v79, v72
	v_add_f32_e32 v72, v80, v72
	v_add_f32_e32 v140, v81, v72
	v_cvt_pk_bf16_f32 v156, v76, v77
	v_cvt_pk_bf16_f32 v157, v78, v79
	s_waitcnt lgkmcnt(11)
	v_mfma_f32_32x32x16_bf16 v[100:115], v[172:175], v[144:147], v[100:115]
	ds_read_b64_tr_b16 v[72:73], v2 offset:37888
	ds_read_b64_tr_b16 v[74:75], v2 offset:38400
	v_add_f32_e32 v76, v82, v140
	v_add_f32_e32 v76, v83, v76
	v_add_f32_e32 v76, v52, v76
	v_add_f32_e32 v140, v53, v76
	v_cvt_pk_bf16_f32 v158, v80, v81
	v_cvt_pk_bf16_f32 v159, v82, v83
	s_waitcnt lgkmcnt(12)
	v_mfma_f32_32x32x16_bf16 v[84:99], v[164:167], v[144:147], v[84:99]
	ds_read_b64_tr_b16 v[76:77], v2 offset:34816
	ds_read_b64_tr_b16 v[78:79], v2 offset:35328
	v_add_f32_e32 v80, v54, v140
	v_add_f32_e32 v80, v55, v80
	v_add_f32_e32 v80, v56, v80
	v_add_f32_e32 v80, v57, v80
	v_cvt_pk_bf16_f32 v148, v52, v53
	v_cvt_pk_bf16_f32 v149, v54, v55
	s_waitcnt lgkmcnt(13)
	v_mfma_f32_32x32x16_bf16 v[100:115], v[128:131], v[136:139], v[100:115]
	ds_read_b64_tr_b16 v[52:53], v2 offset:38912
	ds_read_b64_tr_b16 v[54:55], v2 offset:39424
	v_add_f32_e32 v80, v58, v80
	v_add_f32_e32 v80, v59, v80
	v_add_f32_e32 v80, v60, v80
	v_add_f32_e32 v80, v61, v80
	v_cvt_pk_bf16_f32 v150, v56, v57
	v_cvt_pk_bf16_f32 v151, v58, v59
	s_waitcnt lgkmcnt(14)
	v_mfma_f32_32x32x16_bf16 v[84:99], v[124:127], v[136:139], v[84:99]
	ds_read_b64_tr_b16 v[56:57], v2 offset:35840
	ds_read_b64_tr_b16 v[58:59], v2 offset:36352
	v_add_f32_e32 v80, v62, v80
	v_add_f32_e32 v80, v63, v80
	v_add_f32_e32 v80, v64, v80
	v_add_f32_e32 v80, v65, v80
	v_cvt_pk_bf16_f32 v140, v60, v61
	v_cvt_pk_bf16_f32 v141, v62, v63
	s_waitcnt lgkmcnt(14)
	v_mfma_f32_32x32x16_bf16 v[100:115], v[120:123], v[132:135], v[100:115]
	ds_read_b64_tr_b16 v[60:61], v2 offset:39936
	ds_read_b64_tr_b16 v[62:63], v2 offset:40448
	v_add_f32_e32 v80, v66, v80
	v_add_f32_e32 v80, v67, v80
	v_add_f32_e32 v80, 0, v80
	v_cvt_pk_bf16_f32 v142, v64, v65
	v_cvt_pk_bf16_f32 v143, v66, v67
	v_mfma_f32_32x32x16_bf16 v[84:99], v[116:119], v[132:135], v[84:99]
	v_readlane_b32 s20, v254, 56
	v_readlane_b32 s21, v254, 57
	s_mov_b32 s21, s17
	s_add_i32 s13, s14, s13
	v_lshl_add_u64 v[64:65], v[182:183], 0, s[20:21]
	s_add_i32 s14, s13, 0x4000
	s_mov_b32 s15, m0
	s_mov_b32 m0, s14
	s_nop 0
	global_load_lds_dwordx4 v[64:65], off
	s_mov_b32 m0, s15
	v_add_f32_e32 v191, v191, v80
	v_readlane_b32 s14, v254, 58
	v_readlane_b32 s15, v254, 59
	s_mov_b32 s15, s17
	s_mov_b32 s16, s14
	v_lshl_add_u64 v[64:65], v[180:181], 0, s[14:15]
	s_mov_b32 s14, m0
	s_mov_b32 m0, s8
	s_nop 0
	global_load_lds_dwordx4 v[64:65], off
	s_mov_b32 m0, s14
	v_writelane_b32 v254, s16, 58
	s_nop 1
	v_writelane_b32 v254, s17, 59
	s_waitcnt lgkmcnt(14)
	v_mfma_f32_32x32x16_bf16 v[4:19], v[160:163], v[198:201], v[4:19]
	v_exp_f32_e32 v100, v100
	v_exp_f32_e32 v101, v101
	v_exp_f32_e32 v102, v102
	v_exp_f32_e32 v103, v103
	s_waitcnt lgkmcnt(12)
	v_mfma_f32_32x32x16_bf16 v[20:35], v[160:163], v[176:179], v[20:35]
	v_exp_f32_e32 v104, v104
	v_exp_f32_e32 v105, v105
	v_exp_f32_e32 v106, v106
	v_exp_f32_e32 v107, v107
	ds_read_b128 v[64:67], v189
	ds_read_b128 v[80:83], v189 offset:512
	s_waitcnt lgkmcnt(12)
	v_mfma_f32_32x32x16_bf16 v[4:19], v[156:159], v[68:71], v[4:19]
	v_exp_f32_e32 v108, v108
	v_exp_f32_e32 v109, v109
	v_exp_f32_e32 v110, v110
	v_exp_f32_e32 v111, v111
	ds_read_b128 v[164:167], v189 offset:2048
	ds_read_b128 v[168:171], v189 offset:2560
	s_waitcnt lgkmcnt(12)
	v_mfma_f32_32x32x16_bf16 v[20:35], v[156:159], v[72:75], v[20:35]
	v_exp_f32_e32 v112, v112
	v_exp_f32_e32 v113, v113
	v_exp_f32_e32 v114, v114
	v_exp_f32_e32 v115, v115
	ds_read_b128 v[172:175], v189 offset:4096
	ds_read_b128 v[176:179], v189 offset:4608
	s_waitcnt lgkmcnt(12)
	v_mfma_f32_32x32x16_bf16 v[4:19], v[148:151], v[76:79], v[4:19]
	v_exp_f32_e32 v84, v84
	v_exp_f32_e32 v85, v85
	v_exp_f32_e32 v86, v86
	v_exp_f32_e32 v87, v87
	ds_read_b128 v[198:201], v189 offset:6144
	ds_read_b128 v[72:75], v189 offset:6656
	s_waitcnt lgkmcnt(12)
	v_mfma_f32_32x32x16_bf16 v[20:35], v[148:151], v[52:55], v[20:35]
	v_exp_f32_e32 v88, v88
	v_exp_f32_e32 v89, v89
	v_exp_f32_e32 v90, v90
	v_exp_f32_e32 v91, v91
	s_waitcnt lgkmcnt(10)
	v_mfma_f32_32x32x16_bf16 v[4:19], v[140:143], v[56:59], v[4:19]
	v_exp_f32_e32 v92, v92
	v_exp_f32_e32 v93, v93
	v_exp_f32_e32 v94, v94
	v_exp_f32_e32 v95, v95
	s_waitcnt lgkmcnt(8)
	v_mfma_f32_32x32x16_bf16 v[20:35], v[140:143], v[60:63], v[20:35]
	v_exp_f32_e32 v96, v96
	v_exp_f32_e32 v97, v97
	v_exp_f32_e32 v98, v98
	v_exp_f32_e32 v99, v99
	s_waitcnt vmcnt(2) lgkmcnt(0)
	s_barrier
;   #define RESC() do{ if(resc){ asm volatile("s_waitcnt lgkmcnt(0)":::"memory"); \
;       _Pragma("unroll") for(int d_=0;d_<2;++d_) _Pragma("unroll") for(int r=0;r<16;++r)o[d_][r]*=wsf[crow(r,hi)]; } }while(0)
;   #define ROT() do{sl_prev=sl_cur;sl_cur=sl_next;sl_next=(sl_next==(NSLOT-1)*SLOTB)?0:sl_next+SLOTB;}while(0)
;   #define ENDW(tt) do{ if((tt)+3<NT){WAIT_BAR(2);} else if((tt)+2<NT){WAIT_BAR(1);} else {WAIT_BAR(0);} }while(0)
; template<int THRL,bool NOMAX> __device__ __forceinline__ void attn_unit(int b,int h,int qb,int t0,const bf16*Q,const bf16*__restrict__ KV,const bf16*__restrict__ GA,bf16*O,char*shm){
;     ...
;   for(;t+1<NT;t+=2){
;     STEP(pB0,pB1,pA0,pA1,t,(t+3<NT),(t+1<NT),(t+1<NT));       ENDW(t);   RESC(); ROT();
;     STEP(pA0,pA1,pB0,pB1,t+1,(t+4<NT),(t+2<NT),(t+2<NT));     ENDW(t+1); RESC(); ROT();
	ds_read_b64_tr_b16 v[202:203], v2 offset:40960
	ds_read_b64_tr_b16 v[204:205], v2 offset:41472
	v_add_f32_e32 v52, v100, v101
	v_add_f32_e32 v52, v102, v52
	v_add_f32_e32 v52, v103, v52
	v_add_f32_e32 v52, v104, v52
	v_add_f32_e32 v52, v105, v52
	v_cvt_pk_bf16_f32 v160, v100, v101
	v_cvt_pk_bf16_f32 v161, v102, v103
	s_waitcnt lgkmcnt(9)
	v_mfma_f32_32x32x16_bf16 v[116:131], v[64:67], v[152:155], v[36:51]
	ds_read_b64_tr_b16 v[100:101], v2 offset:45056
	ds_read_b64_tr_b16 v[102:103], v2 offset:45568
	v_add_f32_e32 v52, v106, v52
	v_add_f32_e32 v52, v107, v52
	v_add_f32_e32 v52, v108, v52
	v_add_f32_e32 v76, v109, v52
	v_cvt_pk_bf16_f32 v162, v104, v105
	v_cvt_pk_bf16_f32 v163, v106, v107
	s_waitcnt lgkmcnt(10)
	v_mfma_f32_32x32x16_bf16 v[52:67], v[80:83], v[152:155], v[36:51]
	ds_read_b64_tr_b16 v[68:69], v2 offset:41984
	ds_read_b64_tr_b16 v[70:71], v2 offset:42496
	v_add_f32_e32 v76, v110, v76
	v_add_f32_e32 v76, v111, v76
	v_add_f32_e32 v76, v112, v76
	v_add_f32_e32 v80, v113, v76
	v_cvt_pk_bf16_f32 v156, v108, v109
	v_cvt_pk_bf16_f32 v157, v110, v111
	s_waitcnt lgkmcnt(11)
	v_mfma_f32_32x32x16_bf16 v[116:131], v[164:167], v[144:147], v[116:131]
	ds_read_b64_tr_b16 v[76:77], v2 offset:46080
	ds_read_b64_tr_b16 v[78:79], v2 offset:46592
	v_add_f32_e32 v80, v114, v80
	v_add_f32_e32 v80, v115, v80
	v_add_f32_e32 v80, v84, v80
	v_add_f32_e32 v104, v85, v80
	v_cvt_pk_bf16_f32 v158, v112, v113
	v_cvt_pk_bf16_f32 v159, v114, v115
	s_waitcnt lgkmcnt(12)
	v_mfma_f32_32x32x16_bf16 v[52:67], v[168:171], v[144:147], v[52:67]
	ds_read_b64_tr_b16 v[80:81], v2 offset:43008
	ds_read_b64_tr_b16 v[82:83], v2 offset:43520
	v_add_f32_e32 v104, v86, v104
	v_add_f32_e32 v104, v87, v104
	v_add_f32_e32 v104, v88, v104
	v_add_f32_e32 v108, v89, v104
	v_cvt_pk_bf16_f32 v148, v84, v85
	v_cvt_pk_bf16_f32 v149, v86, v87
	s_waitcnt lgkmcnt(13)
	v_mfma_f32_32x32x16_bf16 v[116:131], v[172:175], v[136:139], v[116:131]
	ds_read_b64_tr_b16 v[104:105], v2 offset:47104
	ds_read_b64_tr_b16 v[106:107], v2 offset:47616
	v_add_f32_e32 v84, v90, v108
	v_add_f32_e32 v84, v91, v84
	v_add_f32_e32 v84, v92, v84
	v_add_f32_e32 v84, v93, v84
	v_cvt_pk_bf16_f32 v150, v88, v89
	v_cvt_pk_bf16_f32 v151, v90, v91
	s_waitcnt lgkmcnt(14)
	v_mfma_f32_32x32x16_bf16 v[52:67], v[176:179], v[136:139], v[52:67]
	ds_read_b64_tr_b16 v[88:89], v2 offset:44032
	ds_read_b64_tr_b16 v[90:91], v2 offset:44544
	v_add_f32_e32 v84, v94, v84
	v_add_f32_e32 v84, v95, v84
	v_add_f32_e32 v84, v96, v84
	v_add_f32_e32 v84, v97, v84
	v_cvt_pk_bf16_f32 v140, v92, v93
	v_cvt_pk_bf16_f32 v141, v94, v95
	s_waitcnt lgkmcnt(14)
	v_mfma_f32_32x32x16_bf16 v[116:131], v[198:201], v[132:135], v[116:131]
	ds_read_b64_tr_b16 v[92:93], v2 offset:48128
	ds_read_b64_tr_b16 v[94:95], v2 offset:48640
	v_mfma_f32_32x32x16_bf16 v[52:67], v[72:75], v[132:135], v[52:67]
	v_add_f32_e32 v72, v98, v84
	v_add_f32_e32 v72, v99, v72
	v_add_f32_e32 v72, 0, v72
	v_cvt_pk_bf16_f32 v142, v96, v97
	v_cvt_pk_bf16_f32 v143, v98, v99
	v_readlane_b32 s22, v254, 60
	v_readlane_b32 s23, v254, 61
	s_mov_b32 s23, s17
	v_add_f32_e32 v191, v191, v72
	v_lshl_add_u64 v[72:73], v[182:183], 0, s[22:23]
	s_mov_b32 s14, m0
	s_mov_b32 m0, s9
	s_nop 0
	global_load_lds_dwordx4 v[72:73], off
	s_mov_b32 m0, s14
	s_add_i32 s9, s13, 0x8000
	v_readlane_b32 s14, v254, 62
	v_readlane_b32 s15, v254, 63
	s_mov_b32 s15, s17
	s_mov_b32 s16, s14
	v_lshl_add_u64 v[72:73], v[180:181], 0, s[14:15]
	s_mov_b32 s14, m0
	s_mov_b32 m0, s9
	s_nop 0
	global_load_lds_dwordx4 v[72:73], off
	s_mov_b32 m0, s14
	v_writelane_b32 v254, s16, 62
	s_nop 1
	v_writelane_b32 v254, s17, 63
	s_waitcnt lgkmcnt(14)
	v_mfma_f32_32x32x16_bf16 v[4:19], v[160:163], v[202:205], v[4:19]
	v_exp_f32_e32 v116, v116
	v_exp_f32_e32 v117, v117
	v_exp_f32_e32 v118, v118
	v_exp_f32_e32 v119, v119
	s_waitcnt lgkmcnt(12)
	v_mfma_f32_32x32x16_bf16 v[20:35], v[160:163], v[100:103], v[20:35]
	v_exp_f32_e32 v120, v120
	v_exp_f32_e32 v121, v121
	v_exp_f32_e32 v122, v122
	v_exp_f32_e32 v123, v123
	ds_read_b128 v[72:75], v189 offset:8192
	ds_read_b128 v[96:99], v189 offset:8704
	s_waitcnt lgkmcnt(12)
	v_mfma_f32_32x32x16_bf16 v[4:19], v[156:159], v[68:71], v[4:19]
	v_exp_f32_e32 v124, v124
	v_exp_f32_e32 v125, v125
	v_exp_f32_e32 v126, v126
	v_exp_f32_e32 v127, v127
	ds_read_b128 v[164:167], v189 offset:10240
	ds_read_b128 v[168:171], v189 offset:10752
	s_waitcnt lgkmcnt(12)
	v_mfma_f32_32x32x16_bf16 v[20:35], v[156:159], v[76:79], v[20:35]
	v_exp_f32_e32 v128, v128
	v_exp_f32_e32 v129, v129
	v_exp_f32_e32 v130, v130
	v_exp_f32_e32 v131, v131
	ds_read_b128 v[172:175], v189 offset:12288
	ds_read_b128 v[176:179], v189 offset:12800
	s_waitcnt lgkmcnt(12)
	v_mfma_f32_32x32x16_bf16 v[4:19], v[148:151], v[80:83], v[4:19]
	v_exp_f32_e32 v52, v52
	v_exp_f32_e32 v53, v53
	v_exp_f32_e32 v54, v54
	v_exp_f32_e32 v55, v55
	ds_read_b128 v[198:201], v189 offset:14336
	ds_read_b128 v[84:87], v189 offset:14848
	s_waitcnt lgkmcnt(12)
	v_mfma_f32_32x32x16_bf16 v[20:35], v[148:151], v[104:107], v[20:35]
	v_exp_f32_e32 v56, v56
	v_exp_f32_e32 v57, v57
	v_exp_f32_e32 v58, v58
	v_exp_f32_e32 v59, v59
	s_waitcnt lgkmcnt(10)
	v_mfma_f32_32x32x16_bf16 v[4:19], v[140:143], v[88:91], v[4:19]
	v_exp_f32_e32 v60, v60
	v_exp_f32_e32 v61, v61
	v_exp_f32_e32 v62, v62
	v_exp_f32_e32 v63, v63
	s_waitcnt lgkmcnt(8)
	v_mfma_f32_32x32x16_bf16 v[20:35], v[140:143], v[92:95], v[20:35]
	v_exp_f32_e32 v64, v64
	v_exp_f32_e32 v65, v65
	v_exp_f32_e32 v66, v66
	v_exp_f32_e32 v67, v67
	s_waitcnt vmcnt(2) lgkmcnt(0)
	s_barrier
;   #define RESC() do{ if(resc){ asm volatile("s_waitcnt lgkmcnt(0)":::"memory"); \
;       _Pragma("unroll") for(int d_=0;d_<2;++d_) _Pragma("unroll") for(int r=0;r<16;++r)o[d_][r]*=wsf[crow(r,hi)]; } }while(0)
;   #define ROT() do{sl_prev=sl_cur;sl_cur=sl_next;sl_next=(sl_next==(NSLOT-1)*SLOTB)?0:sl_next+SLOTB;}while(0)
;   #define ENDW(tt) do{ if((tt)+3<NT){WAIT_BAR(2);} else if((tt)+2<NT){WAIT_BAR(1);} else {WAIT_BAR(0);} }while(0)
; template<int THRL,bool NOMAX> __device__ __forceinline__ void attn_unit(int b,int h,int qb,int t0,const bf16*Q,const bf16*__restrict__ KV,const bf16*__restrict__ GA,bf16*O,char*shm){
;     ...
;   for(;t+1<NT;t+=2){
;     STEP(pB0,pB1,pA0,pA1,t,(t+3<NT),(t+1<NT),(t+1<NT));       ENDW(t);   RESC(); ROT();
;     STEP(pA0,pA1,pB0,pB1,t+1,(t+4<NT),(t+2<NT),(t+2<NT));     ENDW(t+1); RESC(); ROT();
	ds_read_b64_tr_b16 v[88:89], v2 offset:24576
	ds_read_b64_tr_b16 v[90:91], v2 offset:25088
	v_add_f32_e32 v68, v116, v117
	v_add_f32_e32 v68, v118, v68
	v_add_f32_e32 v68, v119, v68
	v_add_f32_e32 v68, v120, v68
	v_add_f32_e32 v68, v121, v68
	v_cvt_pk_bf16_f32 v160, v116, v117
	v_cvt_pk_bf16_f32 v161, v118, v119
	s_waitcnt lgkmcnt(9)
	v_mfma_f32_32x32x16_bf16 v[100:115], v[72:75], v[152:155], v[36:51]
	ds_read_b64_tr_b16 v[92:93], v2 offset:28672
	ds_read_b64_tr_b16 v[94:95], v2 offset:29184
	v_add_f32_e32 v68, v122, v68
	v_add_f32_e32 v68, v123, v68
	v_add_f32_e32 v68, v124, v68
	v_add_f32_e32 v116, v125, v68
	v_cvt_pk_bf16_f32 v162, v120, v121
	v_cvt_pk_bf16_f32 v163, v122, v123
	s_waitcnt lgkmcnt(10)
	v_mfma_f32_32x32x16_bf16 v[68:83], v[96:99], v[152:155], v[36:51]
	ds_read_b64_tr_b16 v[96:97], v2 offset:25600
	ds_read_b64_tr_b16 v[98:99], v2 offset:26112
	v_add_f32_e32 v116, v126, v116
	v_add_f32_e32 v116, v127, v116
	v_add_f32_e32 v116, v128, v116
	v_add_f32_e32 v120, v129, v116
	v_cvt_pk_bf16_f32 v156, v124, v125
	v_cvt_pk_bf16_f32 v157, v126, v127
	s_waitcnt lgkmcnt(11)
	v_mfma_f32_32x32x16_bf16 v[100:115], v[164:167], v[144:147], v[100:115]
	ds_read_b64_tr_b16 v[116:117], v2 offset:29696
	ds_read_b64_tr_b16 v[118:119], v2 offset:30208
	v_add_f32_e32 v120, v130, v120
	v_add_f32_e32 v120, v131, v120
	v_add_f32_e32 v120, v52, v120
	v_add_f32_e32 v124, v53, v120
	v_cvt_pk_bf16_f32 v158, v128, v129
	v_cvt_pk_bf16_f32 v159, v130, v131
	s_waitcnt lgkmcnt(12)
	v_mfma_f32_32x32x16_bf16 v[68:83], v[168:171], v[144:147], v[68:83]
	ds_read_b64_tr_b16 v[120:121], v2 offset:26624
	ds_read_b64_tr_b16 v[122:123], v2 offset:27136
	v_add_f32_e32 v124, v54, v124
	v_add_f32_e32 v124, v55, v124
	v_add_f32_e32 v124, v56, v124
	v_add_f32_e32 v124, v57, v124
	v_cvt_pk_bf16_f32 v148, v52, v53
	v_cvt_pk_bf16_f32 v149, v54, v55
	s_waitcnt lgkmcnt(13)
	v_mfma_f32_32x32x16_bf16 v[100:115], v[172:175], v[136:139], v[100:115]
	ds_read_b64_tr_b16 v[52:53], v2 offset:30720
	ds_read_b64_tr_b16 v[54:55], v2 offset:31232
	v_add_f32_e32 v124, v58, v124
	v_add_f32_e32 v124, v59, v124
	v_add_f32_e32 v124, v60, v124
	v_add_f32_e32 v124, v61, v124
	v_cvt_pk_bf16_f32 v150, v56, v57
	v_cvt_pk_bf16_f32 v151, v58, v59
	s_waitcnt lgkmcnt(14)
	v_mfma_f32_32x32x16_bf16 v[68:83], v[176:179], v[136:139], v[68:83]
	ds_read_b64_tr_b16 v[56:57], v2 offset:27648
	ds_read_b64_tr_b16 v[58:59], v2 offset:28160
	v_add_f32_e32 v124, v62, v124
	v_add_f32_e32 v124, v63, v124
	v_add_f32_e32 v124, v64, v124
	v_add_f32_e32 v124, v65, v124
	v_cvt_pk_bf16_f32 v140, v60, v61
	v_cvt_pk_bf16_f32 v141, v62, v63
	s_waitcnt lgkmcnt(14)
	v_mfma_f32_32x32x16_bf16 v[100:115], v[198:201], v[132:135], v[100:115]
	ds_read_b64_tr_b16 v[60:61], v2 offset:31744
	ds_read_b64_tr_b16 v[62:63], v2 offset:32256
	v_mfma_f32_32x32x16_bf16 v[68:83], v[84:87], v[132:135], v[68:83]
	v_add_f32_e32 v84, v66, v124
	v_add_f32_e32 v84, v67, v84
	v_add_f32_e32 v84, 0, v84
	v_cvt_pk_bf16_f32 v142, v64, v65
	v_cvt_pk_bf16_f32 v143, v66, v67
	s_mov_b32 s14, s20
	v_lshl_add_u64 v[64:65], v[180:181], 0, s[20:21]
	s_add_i32 s13, s13, 0xa000
	s_mov_b32 s9, m0
	s_mov_b32 m0, s13
	s_nop 0
	global_load_lds_dwordx4 v[64:65], off
	s_mov_b32 m0, s9
	v_writelane_b32 v254, s14, 56
	v_add_f32_e32 v182, v191, v84
	s_nop 0
	v_writelane_b32 v254, s15, 57
	s_waitcnt lgkmcnt(14)
	v_mfma_f32_32x32x16_bf16 v[4:19], v[160:163], v[88:91], v[4:19]
	v_exp_f32_e32 v100, v100
	v_exp_f32_e32 v101, v101
	v_exp_f32_e32 v102, v102
	v_exp_f32_e32 v103, v103
	s_waitcnt lgkmcnt(12)
	v_mfma_f32_32x32x16_bf16 v[20:35], v[160:163], v[92:95], v[20:35]
	v_exp_f32_e32 v104, v104
	v_exp_f32_e32 v105, v105
	v_exp_f32_e32 v106, v106
	v_exp_f32_e32 v107, v107
	ds_read_b128 v[64:67], v189 offset:16384
	ds_read_b128 v[124:127], v189 offset:16896
	s_waitcnt lgkmcnt(12)
	v_mfma_f32_32x32x16_bf16 v[4:19], v[156:159], v[96:99], v[4:19]
	v_exp_f32_e32 v108, v108
	v_exp_f32_e32 v109, v109
	v_exp_f32_e32 v110, v110
	v_exp_f32_e32 v111, v111
	ds_read_b128 v[128:131], v189 offset:18432
	ds_read_b128 v[164:167], v189 offset:18944
	s_waitcnt lgkmcnt(12)
	v_mfma_f32_32x32x16_bf16 v[20:35], v[156:159], v[116:119], v[20:35]
	v_exp_f32_e32 v112, v112
	v_exp_f32_e32 v113, v113
	v_exp_f32_e32 v114, v114
	v_exp_f32_e32 v115, v115
	ds_read_b128 v[168:171], v189 offset:20480
	ds_read_b128 v[172:175], v189 offset:20992
	s_waitcnt lgkmcnt(12)
	v_mfma_f32_32x32x16_bf16 v[4:19], v[148:151], v[120:123], v[4:19]
	v_exp_f32_e32 v68, v68
	v_exp_f32_e32 v69, v69
	v_exp_f32_e32 v70, v70
	v_exp_f32_e32 v71, v71
	ds_read_b128 v[120:123], v189 offset:22528
	ds_read_b128 v[116:119], v189 offset:23040
	s_waitcnt lgkmcnt(12)
	v_mfma_f32_32x32x16_bf16 v[20:35], v[148:151], v[52:55], v[20:35]
	v_exp_f32_e32 v72, v72
	v_exp_f32_e32 v73, v73
	v_exp_f32_e32 v74, v74
	v_exp_f32_e32 v75, v75
	s_waitcnt lgkmcnt(10)
	v_mfma_f32_32x32x16_bf16 v[4:19], v[140:143], v[56:59], v[4:19]
	v_exp_f32_e32 v76, v76
	v_exp_f32_e32 v77, v77
	v_exp_f32_e32 v78, v78
	v_exp_f32_e32 v79, v79
	s_waitcnt lgkmcnt(8)
	v_mfma_f32_32x32x16_bf16 v[20:35], v[140:143], v[60:63], v[20:35]
	v_exp_f32_e32 v80, v80
	v_exp_f32_e32 v81, v81
	v_exp_f32_e32 v82, v82
	v_exp_f32_e32 v83, v83
	s_waitcnt vmcnt(1) lgkmcnt(0)
	s_barrier
	ds_read_b64_tr_b16 v[176:177], v2 offset:32768
	ds_read_b64_tr_b16 v[178:179], v2 offset:33280
	v_add_f32_e32 v52, v100, v101
	v_add_f32_e32 v52, v102, v52
	v_add_f32_e32 v52, v103, v52
	v_add_f32_e32 v52, v104, v52
	v_add_f32_e32 v52, v105, v52
	v_cvt_pk_bf16_f32 v160, v100, v101
	v_cvt_pk_bf16_f32 v161, v102, v103
	s_waitcnt lgkmcnt(9)
	v_mfma_f32_32x32x16_bf16 v[84:99], v[64:67], v[152:155], v[36:51]
	ds_read_b64_tr_b16 v[100:101], v2 offset:36864
	ds_read_b64_tr_b16 v[102:103], v2 offset:37376
	v_add_f32_e32 v52, v106, v52
	v_add_f32_e32 v52, v107, v52
	v_add_f32_e32 v52, v108, v52
	v_add_f32_e32 v140, v109, v52
	v_cvt_pk_bf16_f32 v162, v104, v105
	v_cvt_pk_bf16_f32 v163, v106, v107
	s_waitcnt lgkmcnt(10)
	v_mfma_f32_32x32x16_bf16 v[52:67], v[124:127], v[152:155], v[36:51]
	ds_read_b64_tr_b16 v[124:125], v2 offset:33792
	ds_read_b64_tr_b16 v[126:127], v2 offset:34304
	v_add_f32_e32 v104, v110, v140
	v_add_f32_e32 v104, v111, v104
	v_add_f32_e32 v104, v112, v104
	v_add_f32_e32 v104, v113, v104
	v_cvt_pk_bf16_f32 v156, v108, v109
	v_cvt_pk_bf16_f32 v157, v110, v111
	s_waitcnt lgkmcnt(11)
	v_mfma_f32_32x32x16_bf16 v[84:99], v[128:131], v[144:147], v[84:99]
	ds_read_b64_tr_b16 v[106:107], v2 offset:37888
	ds_read_b64_tr_b16 v[108:109], v2 offset:38400
	v_add_f32_e32 v104, v114, v104
	v_add_f32_e32 v104, v115, v104
	v_add_f32_e32 v104, v68, v104
	v_add_f32_e32 v104, v69, v104
	v_cvt_pk_bf16_f32 v158, v112, v113
	v_cvt_pk_bf16_f32 v159, v114, v115
	s_waitcnt lgkmcnt(12)
	v_mfma_f32_32x32x16_bf16 v[52:67], v[164:167], v[144:147], v[52:67]
	ds_read_b64_tr_b16 v[110:111], v2 offset:34816
	ds_read_b64_tr_b16 v[112:113], v2 offset:35328
	v_add_f32_e32 v104, v70, v104
	v_add_f32_e32 v104, v71, v104
	v_add_f32_e32 v104, v72, v104
	v_add_f32_e32 v104, v73, v104
	v_cvt_pk_bf16_f32 v148, v68, v69
	v_cvt_pk_bf16_f32 v149, v70, v71
	s_waitcnt lgkmcnt(13)
	v_mfma_f32_32x32x16_bf16 v[84:99], v[168:171], v[136:139], v[84:99]
	ds_read_b64_tr_b16 v[68:69], v2 offset:38912
	ds_read_b64_tr_b16 v[70:71], v2 offset:39424
	v_add_f32_e32 v104, v74, v104
	v_add_f32_e32 v104, v75, v104
	v_add_f32_e32 v104, v76, v104
	v_add_f32_e32 v104, v77, v104
	v_cvt_pk_bf16_f32 v150, v72, v73
	v_cvt_pk_bf16_f32 v151, v74, v75
	s_waitcnt lgkmcnt(14)
	v_mfma_f32_32x32x16_bf16 v[52:67], v[172:175], v[136:139], v[52:67]
	ds_read_b64_tr_b16 v[72:73], v2 offset:35840
	ds_read_b64_tr_b16 v[74:75], v2 offset:36352
	v_add_f32_e32 v104, v78, v104
	v_add_f32_e32 v104, v79, v104
	v_add_f32_e32 v104, v80, v104
	v_add_f32_e32 v104, v81, v104
	v_cvt_pk_bf16_f32 v140, v76, v77
	v_cvt_pk_bf16_f32 v141, v78, v79
	s_waitcnt lgkmcnt(14)
	v_mfma_f32_32x32x16_bf16 v[84:99], v[120:123], v[132:135], v[84:99]
	ds_read_b64_tr_b16 v[76:77], v2 offset:39936
	ds_read_b64_tr_b16 v[78:79], v2 offset:40448
	v_add_f32_e32 v104, v82, v104
	v_add_f32_e32 v104, v83, v104
	v_add_f32_e32 v104, 0, v104
	v_cvt_pk_bf16_f32 v142, v80, v81
	v_cvt_pk_bf16_f32 v143, v82, v83
	v_mfma_f32_32x32x16_bf16 v[52:67], v[116:119], v[132:135], v[52:67]
	s_mov_b32 s14, s22
	v_lshl_add_u64 v[80:81], v[180:181], 0, s[22:23]
	s_mov_b32 s9, m0
	s_mov_b32 m0, s8
	s_nop 0
	global_load_lds_dwordx4 v[80:81], off
	s_mov_b32 m0, s9
	v_writelane_b32 v254, s14, 60
	v_add_f32_e32 v104, v182, v104
	s_nop 0
	v_writelane_b32 v254, s15, 61
	s_waitcnt lgkmcnt(14)
	v_mfma_f32_32x32x16_bf16 v[4:19], v[160:163], v[176:179], v[4:19]
	v_exp_f32_e32 v84, v84
	v_exp_f32_e32 v85, v85
	v_exp_f32_e32 v86, v86
	v_exp_f32_e32 v87, v87
	s_waitcnt lgkmcnt(12)
	v_mfma_f32_32x32x16_bf16 v[20:35], v[160:163], v[100:103], v[20:35]
	v_exp_f32_e32 v88, v88
	v_exp_f32_e32 v89, v89
	v_exp_f32_e32 v90, v90
	v_exp_f32_e32 v91, v91
	ds_read_b128 v[114:117], v189
	ds_read_b128 v[118:121], v189 offset:512
	s_waitcnt lgkmcnt(12)
	v_mfma_f32_32x32x16_bf16 v[4:19], v[156:159], v[124:127], v[4:19]
	v_exp_f32_e32 v92, v92
	v_exp_f32_e32 v93, v93
	v_exp_f32_e32 v94, v94
	v_exp_f32_e32 v95, v95
	ds_read_b128 v[122:125], v189 offset:2048
	ds_read_b128 v[126:129], v189 offset:2560
	s_waitcnt lgkmcnt(12)
	v_mfma_f32_32x32x16_bf16 v[20:35], v[156:159], v[106:109], v[20:35]
	v_exp_f32_e32 v96, v96
	v_exp_f32_e32 v97, v97
	v_exp_f32_e32 v98, v98
	v_exp_f32_e32 v99, v99
	ds_read_b128 v[106:109], v189 offset:4096
	ds_read_b128 v[164:167], v189 offset:4608
	s_waitcnt lgkmcnt(12)
	v_mfma_f32_32x32x16_bf16 v[4:19], v[148:151], v[110:113], v[4:19]
	v_exp_f32_e32 v52, v52
	v_exp_f32_e32 v53, v53
	v_exp_f32_e32 v54, v54
	v_exp_f32_e32 v55, v55
	ds_read_b128 v[110:113], v189 offset:6144
	ds_read_b128 v[100:103], v189 offset:6656
	s_waitcnt lgkmcnt(12)
	v_mfma_f32_32x32x16_bf16 v[20:35], v[148:151], v[68:71], v[20:35]
	v_exp_f32_e32 v56, v56
	v_exp_f32_e32 v57, v57
	v_exp_f32_e32 v58, v58
	v_exp_f32_e32 v59, v59
	s_waitcnt lgkmcnt(10)
	v_mfma_f32_32x32x16_bf16 v[4:19], v[140:143], v[72:75], v[4:19]
	v_exp_f32_e32 v60, v60
	v_exp_f32_e32 v61, v61
	v_exp_f32_e32 v62, v62
	v_exp_f32_e32 v63, v63
	s_waitcnt lgkmcnt(8)
	v_mfma_f32_32x32x16_bf16 v[20:35], v[140:143], v[76:79], v[20:35]
	v_exp_f32_e32 v64, v64
	v_exp_f32_e32 v65, v65
	v_exp_f32_e32 v66, v66
	v_exp_f32_e32 v67, v67
	s_waitcnt vmcnt(0) lgkmcnt(0)
	s_barrier
	ds_read_b64_tr_b16 v[168:169], v2 offset:40960
	ds_read_b64_tr_b16 v[170:171], v2 offset:41472
	v_add_f32_e32 v68, v84, v85
	v_add_f32_e32 v68, v86, v68
	v_add_f32_e32 v68, v87, v68
	v_add_f32_e32 v68, v88, v68
	v_add_f32_e32 v105, v89, v68
	v_cvt_pk_bf16_f32 v160, v84, v85
	v_cvt_pk_bf16_f32 v161, v86, v87
	s_waitcnt lgkmcnt(9)
	v_mfma_f32_32x32x16_bf16 v[68:83], v[114:117], v[152:155], v[36:51]
	ds_read_b64_tr_b16 v[84:85], v2 offset:45056
	ds_read_b64_tr_b16 v[86:87], v2 offset:45568
	s_waitcnt lgkmcnt(10)
	v_mfma_f32_32x32x16_bf16 v[36:51], v[118:121], v[152:155], v[36:51]
	v_add_f32_e32 v105, v90, v105
	v_add_f32_e32 v105, v91, v105
	v_add_f32_e32 v105, v92, v105
	v_add_f32_e32 v105, v93, v105
	v_cvt_pk_bf16_f32 v162, v88, v89
	v_cvt_pk_bf16_f32 v163, v90, v91
	ds_read_b64_tr_b16 v[88:89], v2 offset:41984
	ds_read_b64_tr_b16 v[90:91], v2 offset:42496
	v_add_f32_e32 v105, v94, v105
	v_add_f32_e32 v105, v95, v105
	v_add_f32_e32 v105, v96, v105
	v_add_f32_e32 v105, v97, v105
	v_cvt_pk_bf16_f32 v156, v92, v93
	v_cvt_pk_bf16_f32 v157, v94, v95
	s_waitcnt lgkmcnt(11)
	v_mfma_f32_32x32x16_bf16 v[68:83], v[122:125], v[144:147], v[68:83]
	ds_read_b64_tr_b16 v[92:93], v2 offset:46080
	ds_read_b64_tr_b16 v[94:95], v2 offset:46592
	s_waitcnt lgkmcnt(12)
	v_mfma_f32_32x32x16_bf16 v[36:51], v[126:129], v[144:147], v[36:51]
	v_add_f32_e32 v105, v98, v105
	v_add_f32_e32 v105, v99, v105
	v_add_f32_e32 v105, v52, v105
	v_add_f32_e32 v105, v53, v105
	v_cvt_pk_bf16_f32 v158, v96, v97
	v_cvt_pk_bf16_f32 v159, v98, v99
	ds_read_b64_tr_b16 v[96:97], v2 offset:43008
	ds_read_b64_tr_b16 v[98:99], v2 offset:43520
	v_add_f32_e32 v105, v54, v105
	v_add_f32_e32 v105, v55, v105
	v_add_f32_e32 v105, v56, v105
	v_add_f32_e32 v105, v57, v105
	v_cvt_pk_bf16_f32 v148, v52, v53
	v_cvt_pk_bf16_f32 v149, v54, v55
	s_waitcnt lgkmcnt(13)
	v_mfma_f32_32x32x16_bf16 v[68:83], v[106:109], v[136:139], v[68:83]
	ds_read_b64_tr_b16 v[52:53], v2 offset:47104
	ds_read_b64_tr_b16 v[54:55], v2 offset:47616
	s_waitcnt lgkmcnt(14)
	v_mfma_f32_32x32x16_bf16 v[36:51], v[164:167], v[136:139], v[36:51]
	v_add_f32_e32 v105, v58, v105
	v_add_f32_e32 v105, v59, v105
	v_add_f32_e32 v105, v60, v105
	v_add_f32_e32 v105, v61, v105
	v_cvt_pk_bf16_f32 v150, v56, v57
	v_cvt_pk_bf16_f32 v151, v58, v59
	ds_read_b64_tr_b16 v[56:57], v2 offset:44032
	ds_read_b64_tr_b16 v[58:59], v2 offset:44544
	v_add_f32_e32 v105, v62, v105
	v_add_f32_e32 v105, v63, v105
	v_add_f32_e32 v105, v64, v105
	v_add_f32_e32 v105, v65, v105
	v_cvt_pk_bf16_f32 v140, v60, v61
	v_cvt_pk_bf16_f32 v141, v62, v63
	s_waitcnt lgkmcnt(14)
	v_mfma_f32_32x32x16_bf16 v[68:83], v[110:113], v[132:135], v[68:83]
	ds_read_b64_tr_b16 v[60:61], v2 offset:48128
	ds_read_b64_tr_b16 v[62:63], v2 offset:48640
	v_mfma_f32_32x32x16_bf16 v[36:51], v[100:103], v[132:135], v[36:51]
	v_add_f32_e32 v2, v66, v105
	v_add_f32_e32 v2, v67, v2
	v_add_f32_e32 v2, 0, v2
	v_cvt_pk_bf16_f32 v142, v64, v65
	v_cvt_pk_bf16_f32 v143, v66, v67
	s_waitcnt lgkmcnt(14)
	v_mfma_f32_32x32x16_bf16 v[4:19], v[160:163], v[168:171], v[4:19]
	s_nop 1
	v_exp_f32_e32 v68, v68
	v_exp_f32_e32 v69, v69
	v_exp_f32_e32 v70, v70
	v_exp_f32_e32 v71, v71
	s_waitcnt lgkmcnt(12)
	v_mfma_f32_32x32x16_bf16 v[20:35], v[160:163], v[84:87], v[20:35]
	v_exp_f32_e32 v72, v72
	v_exp_f32_e32 v73, v73
	v_exp_f32_e32 v74, v74
	v_exp_f32_e32 v75, v75
	s_waitcnt lgkmcnt(10)
	v_mfma_f32_32x32x16_bf16 v[4:19], v[156:159], v[88:91], v[4:19]
	v_exp_f32_e32 v76, v76
	v_exp_f32_e32 v77, v77
	v_exp_f32_e32 v78, v78
	v_exp_f32_e32 v79, v79
	s_waitcnt lgkmcnt(8)
	v_mfma_f32_32x32x16_bf16 v[20:35], v[156:159], v[92:95], v[20:35]
	v_exp_f32_e32 v80, v80
	v_exp_f32_e32 v81, v81
	v_exp_f32_e32 v82, v82
	v_exp_f32_e32 v83, v83
	s_waitcnt lgkmcnt(6)
; #define SBAR() __builtin_amdgcn_sched_barrier(0)
;   #define PKW(P,B) cvtpk_s(P[B],P[B+1])
; __device__ __forceinline__ void pv(f32x16*o,int vb,bf16x8 pa0,bf16x8 pa1,bf16x8 pa2,bf16x8 pa3){
;   #pragma unroll
;   for(int d0=0;d0<2;++d0){s16x4 lo[4],hi[4];
;     #pragma unroll
;     for(int ks=0;ks<4;++ks){
;       asm volatile("ds_read_b64_tr_b16 %0,%1 offset:%c2":"=&v"(lo[ks]):"v"(vb),"i"(d0*4096+ks*1024):"memory");
;       asm volatile("ds_read_b64_tr_b16 %0,%1 offset:%c2":"=&v"(hi[ks]):"v"(vb),"i"(d0*4096+ks*1024+512):"memory");}
;     asm volatile("s_waitcnt lgkmcnt(0)":::"memory");SBAR();
;     ...
;     o[d0]=__builtin_amdgcn_mfma_f32_32x32x16_bf16(pa0,PK(0),o[d0],0,0,0);
;     o[d0]=__builtin_amdgcn_mfma_f32_32x32x16_bf16(pa1,PK(1),o[d0],0,0,0);
;     o[d0]=__builtin_amdgcn_mfma_f32_32x32x16_bf16(pa2,PK(2),o[d0],0,0,0);
;     o[d0]=__builtin_amdgcn_mfma_f32_32x32x16_bf16(pa3,PK(3),o[d0],0,0,0);
;     ...
;   }
; }
; template<int THRL,bool NOMAX> __device__ __forceinline__ void attn_unit(int b,int h,int qb,int t0,const bf16*Q,const bf16*__restrict__ KV,const bf16*__restrict__ GA,bf16*O,char*shm){
;     ...
;   { float sacc=pB0[0]+pB0[1]; _Pragma("unroll") for(int r=2;r<16;++r)sacc+=pB0[r]; _Pragma("unroll") for(int r=0;r<16;++r)sacc+=pB1[r]; l_reg+=sacc;
;     pw0=(u32x4){PKW(pB0,0),PKW(pB0,2),PKW(pB0,4),PKW(pB0,6)};pw1=(u32x4){PKW(pB0,8),PKW(pB0,10),PKW(pB0,12),PKW(pB0,14)};pw2=(u32x4){PKW(pB1,0),PKW(pB1,2),PKW(pB1,4),PKW(pB1,6)};pw3=(u32x4){PKW(pB1,8),PKW(pB1,10),PKW(pB1,12),PKW(pB1,14)};
;     SBAR(); pv(o,vb0+sl_cur,PAF(0),PAF(1),PAF(2),PAF(3)); }
;     ...
;   {auto rr=__builtin_amdgcn_permlane32_swap(__float_as_uint(l_reg),__float_as_uint(l_reg),false,false);l_reg=__uint_as_float(rr[0])+__uint_as_float(rr[1]);}
;   if(hi==0)wsf[32+r32]=l_reg;asm volatile("s_waitcnt lgkmcnt(0)":::"memory");
	v_mfma_f32_32x32x16_bf16 v[4:19], v[148:151], v[96:99], v[4:19]
	v_exp_f32_e32 v36, v36
	v_exp_f32_e32 v37, v37
	v_exp_f32_e32 v38, v38
	v_exp_f32_e32 v39, v39
	s_waitcnt lgkmcnt(4)
	v_mfma_f32_32x32x16_bf16 v[20:35], v[148:151], v[52:55], v[20:35]
	v_exp_f32_e32 v40, v40
	v_exp_f32_e32 v41, v41
	v_exp_f32_e32 v42, v42
	v_exp_f32_e32 v43, v43
	s_waitcnt lgkmcnt(2)
	v_mfma_f32_32x32x16_bf16 v[4:19], v[140:143], v[56:59], v[4:19]
	v_exp_f32_e32 v44, v44
	v_exp_f32_e32 v45, v45
	v_exp_f32_e32 v46, v46
	v_exp_f32_e32 v47, v47
	s_waitcnt lgkmcnt(0)
	v_mfma_f32_32x32x16_bf16 v[20:35], v[140:143], v[60:63], v[20:35]
	v_exp_f32_e32 v48, v48
	v_exp_f32_e32 v49, v49
	v_exp_f32_e32 v50, v50
	v_exp_f32_e32 v51, v51
	v_add_f32_e32 v52, v68, v69
	v_add_f32_e32 v52, v70, v52
	v_add_f32_e32 v52, v71, v52
	v_add_f32_e32 v52, v72, v52
	v_add_f32_e32 v52, v73, v52
	v_add_f32_e32 v52, v74, v52
	v_add_f32_e32 v52, v75, v52
	v_add_f32_e32 v52, v76, v52
	v_add_f32_e32 v52, v77, v52
	v_add_f32_e32 v52, v78, v52
	v_add_f32_e32 v52, v79, v52
	v_add_f32_e32 v52, v80, v52
	v_add_f32_e32 v52, v81, v52
	v_add_f32_e32 v52, v82, v52
	v_add_f32_e32 v52, v83, v52
	v_add_f32_e32 v52, v36, v52
	v_add_f32_e32 v52, v37, v52
	v_add_f32_e32 v52, v38, v52
	v_add_f32_e32 v52, v39, v52
	v_add_f32_e32 v52, v40, v52
	v_add_f32_e32 v52, v41, v52
	v_add_f32_e32 v52, v42, v52
	v_add_f32_e32 v52, v43, v52
	v_add_f32_e32 v52, v44, v52
	v_add_f32_e32 v52, v45, v52
	v_add_f32_e32 v52, v46, v52
	v_add_f32_e32 v52, v47, v52
	v_add_f32_e32 v52, v48, v52
	v_add_f32_e32 v52, v49, v52
	v_add_f32_e32 v52, v50, v52
	v_add_f32_e32 v52, v51, v52
	v_add_f32_e32 v2, v104, v2
	v_add_f32_e32 v2, v2, v52
	v_cvt_pk_bf16_f32 v36, v36, v37
	v_cvt_pk_bf16_f32 v52, v68, v69
	v_cvt_pk_bf16_f32 v53, v70, v71
	v_cvt_pk_bf16_f32 v54, v72, v73
	v_cvt_pk_bf16_f32 v55, v74, v75
	v_cvt_pk_bf16_f32 v56, v76, v77
	v_cvt_pk_bf16_f32 v57, v78, v79
	v_cvt_pk_bf16_f32 v58, v80, v81
	v_cvt_pk_bf16_f32 v59, v82, v83
	v_cvt_pk_bf16_f32 v37, v38, v39
	v_cvt_pk_bf16_f32 v38, v40, v41
	v_cvt_pk_bf16_f32 v39, v42, v43
	v_cvt_pk_bf16_f32 v40, v44, v45
	v_cvt_pk_bf16_f32 v41, v46, v47
	v_cvt_pk_bf16_f32 v42, v48, v49
	v_cvt_pk_bf16_f32 v43, v50, v51
	ds_read_b64_tr_b16 v[44:45],v190 offset:0
	ds_read_b64_tr_b16 v[46:47],v190 offset:512
	ds_read_b64_tr_b16 v[48:49],v190 offset:1024
	ds_read_b64_tr_b16 v[50:51],v190 offset:1536
	ds_read_b64_tr_b16 v[60:61],v190 offset:2048
	ds_read_b64_tr_b16 v[62:63],v190 offset:2560
	ds_read_b64_tr_b16 v[64:65],v190 offset:3072
	ds_read_b64_tr_b16 v[66:67],v190 offset:3584
	s_waitcnt lgkmcnt(0)
	s_nop 0
	v_mfma_f32_32x32x16_bf16 v[4:19], v[52:55], v[44:47], v[4:19]
	ds_read_b64_tr_b16 v[44:45],v190 offset:4096
	ds_read_b64_tr_b16 v[46:47],v190 offset:4608
	v_mfma_f32_32x32x16_bf16 v[4:19], v[56:59], v[48:51], v[4:19]
	ds_read_b64_tr_b16 v[48:49],v190 offset:5120
	ds_read_b64_tr_b16 v[50:51],v190 offset:5632
	v_mfma_f32_32x32x16_bf16 v[4:19], v[36:39], v[60:63], v[4:19]
	ds_read_b64_tr_b16 v[60:61],v190 offset:6144
	ds_read_b64_tr_b16 v[62:63],v190 offset:6656
	v_mfma_f32_32x32x16_bf16 v[4:19], v[40:43], v[64:67], v[4:19]
	ds_read_b64_tr_b16 v[64:65],v190 offset:7168
	ds_read_b64_tr_b16 v[66:67],v190 offset:7680
	s_waitcnt lgkmcnt(0)
	v_mfma_f32_32x32x16_bf16 v[20:35], v[52:55], v[44:47], v[20:35]
	v_cmp_gt_u32_e32 vcc, 32, v184
	v_mfma_f32_32x32x16_bf16 v[20:35], v[56:59], v[48:51], v[20:35]
	v_mfma_f32_32x32x16_bf16 v[20:35], v[36:39], v[60:63], v[20:35]
	v_mov_b32_e32 v36, v2
	s_nop 1
	v_permlane32_swap_b32_e32 v2, v36
	v_mfma_f32_32x32x16_bf16 v[20:35], v[40:43], v[64:67], v[20:35]
	s_and_saveexec_b64 s[8:9], vcc
	s_cbranch_execz .LBB0_470
	v_lshl_add_u32 v37, v185, 2, s12
	v_add_f32_e32 v2, v2, v36
	ds_write_b32 v37, v2 offset:49280
	s_branch .LBB0_470
